# adds: GEMM K-loop back-edge SALU block (counter, pointers, compare) moved above the iteration's last s_barrier in 9 of 16 K-loops
# baseline (speedup 1.0000x reference)
; #define PG8_STAGE(bufoff, gbase, voff) do { _Pragma("unroll") for (int _i = 0; _i < 2; ++_i) \
;         __builtin_amdgcn_global_load_lds((const unsigned*)((const char*)(gbase) + (voff)[_i]), (PG8_LAS unsigned*)(lds + (bufoff) + ldsw + _i * 8192), 16, 0, 0); } while (0)
; #define PG8_LDA(dst, b, h) do { _Pragma("unroll") for (int m = 0; m < 4; ++m) _Pragma("unroll") for (int k = 0; k < 2; ++k) dst[m][k] = *(const PG8_LAS bf16x8*)(lds + PG8_SA(b, h) + aoff + m * 2048 + k * 1024); } while (0)
; #define PG8_LDB(dst, b, h) do { _Pragma("unroll") for (int n = 0; n < 2; ++n) _Pragma("unroll") for (int k = 0; k < 2; ++k) dst[n][k] = *(const PG8_LAS bf16x8*)(lds + PG8_SB(b, h) + boff + n * 2048 + k * 1024); } while (0)
; #define PG8_MMA(ai, bj, At, Bt) do { __builtin_amdgcn_s_setprio(1); _Pragma("unroll") for (int m = 0; m < 4; ++m) _Pragma("unroll") for (int n = 0; n < 2; ++n) _Pragma("unroll") for (int k = 0; k < 2; ++k) \
;         acc[ai][bj][m][n] = __builtin_amdgcn_mfma_f32_16x16x32_bf16(Bt[n][k], At[m][k], acc[ai][bj][m][n], 0, 0, 0); __builtin_amdgcn_s_setprio(0); } while (0)
; #define PG8_WAIT_V(n) asm volatile("s_waitcnt vmcnt(" #n ")" ::: "memory")
; #define PG8_WAIT_L(n) asm volatile("s_waitcnt lgkmcnt(" #n ")" ::: "memory")
; #define PG8_BAR __builtin_amdgcn_s_barrier()
; template <class Epi, class Sched, bool ALIGN_EPI = false, bool SP2 = false>
; __device__ __forceinline__ void gemm_phase(PG8_LAS unsigned char* lds, const Gemm g, const Sched& S, const Epi& E, const int wave_in) {
;     ...
;         for (int t = 0; t < nt; t += 2) {
;             const bool last = (t == nt - 2);
;             const char* a1 = cA + (size_t)(t + 1) * kstep;
;             const char* a2 = last ? nA : cA + (size_t)(t + 2) * kstep; const char* b2 = last ? nB : cB + (size_t)(t + 2) * kstep;
;             const char* a3 = a2 + kstep; const char* b3 = b2 + kstep;
;             if (last && has_next) S.a_ready(nxt);
;             if constexpr (SP2) {
;             PG8_LDB(B0, 0, 0); PG8_LDB(B1, 0, 1); PG8_SCHED; PG8_LDA(At, 0, 0); PG8_STAGE(PG8_SA(1, 1), a1 + hstepA, voffA);
;             PG8_WAIT_V(8); PG8_WAIT_L(0); PG8_BAR; PG8_MMA(0, 0, At, B0); PG8_MMA(0, 1, At, B1); PG8_BAR; PG8_SCHED;
;             PG8_LDA(At, 0, 1); PG8_STAGE(PG8_SB(0, 0), b2, voffB); PG8_STAGE(PG8_SB(0, 1), b2 + hstepB, voffB); PG8_STAGE(PG8_SA(0, 0), a2, voffA);
.LBB0_158:
	ds_read_b128 v[144:147], v151
	ds_read_b128 v[154:157], v151 offset:1024
	ds_read_b128 v[158:161], v151 offset:2048
	ds_read_b128 v[162:165], v151 offset:3072
	ds_read_b128 v[166:169], v152
	ds_read_b128 v[170:173], v152 offset:1024
	ds_read_b128 v[174:177], v152 offset:2048
	ds_read_b128 v[178:181], v152 offset:3072
	s_add_u32 s24, s22, 0xfff80080
	s_addc_u32 s25, s23, -1
	s_cmp_eq_u32 s49, 28
	s_cselect_b32 s27, s5, s25
	s_cselect_b32 s26, s15, s24
	s_cselect_b32 s25, s13, s48
	s_cselect_b32 s24, s46, s47
	v_lshl_add_u64 v[214:215], s[22:23], 0, v[136:137]
	s_add_i32 m0, s21, 0xc000
	ds_read_b128 v[182:185], v153
	ds_read_b128 v[186:189], v153 offset:1024
	ds_read_b128 v[190:193], v153 offset:2048
	ds_read_b128 v[194:197], v153 offset:3072
	ds_read_b128 v[198:201], v153 offset:4096
	ds_read_b128 v[202:205], v153 offset:5120
	ds_read_b128 v[206:209], v153 offset:6144
	ds_read_b128 v[210:213], v153 offset:7168
	global_load_lds_dwordx4 v[214:215], off
	v_lshl_add_u64 v[214:215], s[22:23], 0, v[138:139]
	s_add_i32 m0, s21, 0xe000
	s_nop 0
	global_load_lds_dwordx4 v[214:215], off
	s_waitcnt vmcnt(8)
	s_waitcnt lgkmcnt(0)
	s_barrier
	s_setprio 1
	s_waitcnt lgkmcnt(0)
	v_mfma_f32_16x16x32_bf16 v[124:127], v[144:147], v[182:185], v[124:127]
	v_mfma_f32_16x16x32_bf16 v[120:123], v[158:161], v[182:185], v[120:123]
	v_mfma_f32_16x16x32_bf16 v[108:111], v[144:147], v[190:193], v[108:111]
	v_mfma_f32_16x16x32_bf16 v[104:107], v[158:161], v[190:193], v[104:107]
	v_mfma_f32_16x16x32_bf16 v[92:95], v[144:147], v[198:201], v[92:95]
	v_mfma_f32_16x16x32_bf16 v[88:91], v[158:161], v[198:201], v[88:91]
	v_mfma_f32_16x16x32_bf16 v[76:79], v[144:147], v[206:209], v[76:79]
	v_mfma_f32_16x16x32_bf16 v[72:75], v[158:161], v[206:209], v[72:75]
	v_mfma_f32_16x16x32_bf16 v[124:127], v[154:157], v[186:189], v[124:127]
	v_mfma_f32_16x16x32_bf16 v[120:123], v[162:165], v[186:189], v[120:123]
	v_mfma_f32_16x16x32_bf16 v[108:111], v[154:157], v[194:197], v[108:111]
	v_mfma_f32_16x16x32_bf16 v[104:107], v[162:165], v[194:197], v[104:107]
	v_mfma_f32_16x16x32_bf16 v[92:95], v[154:157], v[202:205], v[92:95]
	v_mfma_f32_16x16x32_bf16 v[88:91], v[162:165], v[202:205], v[88:91]
	v_mfma_f32_16x16x32_bf16 v[76:79], v[154:157], v[210:213], v[76:79]
	v_mfma_f32_16x16x32_bf16 v[72:75], v[162:165], v[210:213], v[72:75]
	s_setprio 0
	s_setprio 1
	v_mfma_f32_16x16x32_bf16 v[116:119], v[166:169], v[182:185], v[116:119]
	v_mfma_f32_16x16x32_bf16 v[112:115], v[174:177], v[182:185], v[112:115]
	v_mfma_f32_16x16x32_bf16 v[100:103], v[166:169], v[190:193], v[100:103]
	v_mfma_f32_16x16x32_bf16 v[96:99], v[174:177], v[190:193], v[96:99]
	v_mfma_f32_16x16x32_bf16 v[84:87], v[166:169], v[198:201], v[84:87]
	v_mfma_f32_16x16x32_bf16 v[80:83], v[174:177], v[198:201], v[80:83]
	v_mfma_f32_16x16x32_bf16 v[68:71], v[166:169], v[206:209], v[68:71]
	v_mfma_f32_16x16x32_bf16 v[64:67], v[174:177], v[206:209], v[64:67]
	v_mfma_f32_16x16x32_bf16 v[116:119], v[170:173], v[186:189], v[116:119]
	v_mfma_f32_16x16x32_bf16 v[112:115], v[178:181], v[186:189], v[112:115]
	v_mfma_f32_16x16x32_bf16 v[100:103], v[170:173], v[194:197], v[100:103]
	v_mfma_f32_16x16x32_bf16 v[96:99], v[178:181], v[194:197], v[96:99]
	v_mfma_f32_16x16x32_bf16 v[84:87], v[170:173], v[202:205], v[84:87]
	v_mfma_f32_16x16x32_bf16 v[80:83], v[178:181], v[202:205], v[80:83]
	v_mfma_f32_16x16x32_bf16 v[68:71], v[170:173], v[210:213], v[68:71]
	v_mfma_f32_16x16x32_bf16 v[64:67], v[178:181], v[210:213], v[64:67]
	s_setprio 0
	s_barrier
	s_add_i32 s50, s43, s34
	v_lshl_add_u64 v[214:215], s[24:25], 0, v[130:131]
	s_mov_b32 m0, s50
	ds_read_b128 v[182:185], v153 offset:16384
	ds_read_b128 v[186:189], v153 offset:17408
	ds_read_b128 v[190:193], v153 offset:18432
	ds_read_b128 v[194:197], v153 offset:19456
	ds_read_b128 v[198:201], v153 offset:20480
	ds_read_b128 v[202:205], v153 offset:21504
	ds_read_b128 v[206:209], v153 offset:22528
	ds_read_b128 v[210:213], v153 offset:23552
	global_load_lds_dwordx4 v[214:215], off
	s_add_i32 m0, s50, 0x2000
	s_add_u32 s50, s24, 0x80000
	v_lshl_add_u64 v[216:217], s[24:25], 0, v[134:135]
	s_addc_u32 s51, s25, 0
	s_add_i32 s52, s44, s34
	global_load_lds_dwordx4 v[216:217], off
	v_lshl_add_u64 v[218:219], s[50:51], 0, v[130:131]
	s_mov_b32 m0, s52
	v_lshl_add_u64 v[220:221], s[26:27], 0, v[132:133]
	global_load_lds_dwordx4 v[218:219], off
	v_lshl_add_u64 v[218:219], s[50:51], 0, v[134:135]
	s_add_i32 m0, s52, 0x2000
	s_nop 0
	global_load_lds_dwordx4 v[218:219], off
	v_lshl_add_u64 v[218:219], s[26:27], 0, v[128:129]
	s_mov_b32 m0, s21
	s_nop 0
	global_load_lds_dwordx4 v[218:219], off
	s_mov_b32 m0, s35
	s_nop 0
	global_load_lds_dwordx4 v[220:221], off
	s_waitcnt vmcnt(8)
	s_waitcnt lgkmcnt(0)
	s_barrier
; #define PG8_STAGE(bufoff, gbase, voff) do { _Pragma("unroll") for (int _i = 0; _i < 2; ++_i) \
;         __builtin_amdgcn_global_load_lds((const unsigned*)((const char*)(gbase) + (voff)[_i]), (PG8_LAS unsigned*)(lds + (bufoff) + ldsw + _i * 8192), 16, 0, 0); } while (0)
; #define PG8_LDA(dst, b, h) do { _Pragma("unroll") for (int m = 0; m < 4; ++m) _Pragma("unroll") for (int k = 0; k < 2; ++k) dst[m][k] = *(const PG8_LAS bf16x8*)(lds + PG8_SA(b, h) + aoff + m * 2048 + k * 1024); } while (0)
; #define PG8_LDB(dst, b, h) do { _Pragma("unroll") for (int n = 0; n < 2; ++n) _Pragma("unroll") for (int k = 0; k < 2; ++k) dst[n][k] = *(const PG8_LAS bf16x8*)(lds + PG8_SB(b, h) + boff + n * 2048 + k * 1024); } while (0)
; #define PG8_MMA(ai, bj, At, Bt) do { __builtin_amdgcn_s_setprio(1); _Pragma("unroll") for (int m = 0; m < 4; ++m) _Pragma("unroll") for (int n = 0; n < 2; ++n) _Pragma("unroll") for (int k = 0; k < 2; ++k) \
;         acc[ai][bj][m][n] = __builtin_amdgcn_mfma_f32_16x16x32_bf16(Bt[n][k], At[m][k], acc[ai][bj][m][n], 0, 0, 0); __builtin_amdgcn_s_setprio(0); } while (0)
; #define PG8_WAIT_V(n) asm volatile("s_waitcnt vmcnt(" #n ")" ::: "memory")
; #define PG8_WAIT_L(n) asm volatile("s_waitcnt lgkmcnt(" #n ")" ::: "memory")
; #define PG8_BAR __builtin_amdgcn_s_barrier()
; #define PG8_SCHED __builtin_amdgcn_sched_barrier(0)
; template <class Epi, class Sched, bool ALIGN_EPI = false, bool SP2 = false>
; __device__ __forceinline__ void gemm_phase(PG8_LAS unsigned char* lds, const Gemm g, const Sched& S, const Epi& E, const int wave_in) {
;     ...
;             PG8_WAIT_V(8); PG8_WAIT_L(0); PG8_BAR; PG8_MMA(1, 0, At, B0); PG8_MMA(1, 1, At, B1); PG8_BAR; PG8_SCHED;
;             PG8_LDB(B0, 1, 0); PG8_LDB(B1, 1, 1); PG8_SCHED; PG8_LDA(At, 1, 0); PG8_STAGE(PG8_SA(0, 1), a2 + hstepA, voffA);
;             PG8_WAIT_V(8); PG8_WAIT_L(0); PG8_BAR; PG8_MMA(0, 0, At, B0); PG8_MMA(0, 1, At, B1); PG8_BAR; PG8_SCHED;
	s_setprio 1
	s_waitcnt lgkmcnt(0)
	v_mfma_f32_16x16x32_bf16 v[60:63], v[144:147], v[182:185], v[60:63]
	v_mfma_f32_16x16x32_bf16 v[56:59], v[158:161], v[182:185], v[56:59]
	v_mfma_f32_16x16x32_bf16 v[44:47], v[144:147], v[190:193], v[44:47]
	v_mfma_f32_16x16x32_bf16 v[40:43], v[158:161], v[190:193], v[40:43]
	v_mfma_f32_16x16x32_bf16 v[28:31], v[144:147], v[198:201], v[28:31]
	v_mfma_f32_16x16x32_bf16 v[24:27], v[158:161], v[198:201], v[24:27]
	v_mfma_f32_16x16x32_bf16 v[12:15], v[144:147], v[206:209], v[12:15]
	v_mfma_f32_16x16x32_bf16 v[8:11], v[158:161], v[206:209], v[8:11]
	v_mfma_f32_16x16x32_bf16 v[60:63], v[154:157], v[186:189], v[60:63]
	v_mfma_f32_16x16x32_bf16 v[56:59], v[162:165], v[186:189], v[56:59]
	v_mfma_f32_16x16x32_bf16 v[44:47], v[154:157], v[194:197], v[44:47]
	v_mfma_f32_16x16x32_bf16 v[40:43], v[162:165], v[194:197], v[40:43]
	v_mfma_f32_16x16x32_bf16 v[28:31], v[154:157], v[202:205], v[28:31]
	v_mfma_f32_16x16x32_bf16 v[24:27], v[162:165], v[202:205], v[24:27]
	v_mfma_f32_16x16x32_bf16 v[12:15], v[154:157], v[210:213], v[12:15]
	v_mfma_f32_16x16x32_bf16 v[8:11], v[162:165], v[210:213], v[8:11]
	s_setprio 0
	s_setprio 1
	v_mfma_f32_16x16x32_bf16 v[52:55], v[166:169], v[182:185], v[52:55]
	v_mfma_f32_16x16x32_bf16 v[48:51], v[174:177], v[182:185], v[48:51]
	v_mfma_f32_16x16x32_bf16 v[36:39], v[166:169], v[190:193], v[36:39]
	v_mfma_f32_16x16x32_bf16 v[32:35], v[174:177], v[190:193], v[32:35]
	v_mfma_f32_16x16x32_bf16 v[20:23], v[166:169], v[198:201], v[20:23]
	v_mfma_f32_16x16x32_bf16 v[16:19], v[174:177], v[198:201], v[16:19]
	v_mfma_f32_16x16x32_bf16 v[4:7], v[166:169], v[206:209], v[4:7]
	v_mfma_f32_16x16x32_bf16 v[0:3], v[174:177], v[206:209], v[0:3]
	v_mfma_f32_16x16x32_bf16 v[52:55], v[170:173], v[186:189], v[52:55]
	v_mfma_f32_16x16x32_bf16 v[48:51], v[178:181], v[186:189], v[48:51]
	v_mfma_f32_16x16x32_bf16 v[36:39], v[170:173], v[194:197], v[36:39]
	v_mfma_f32_16x16x32_bf16 v[32:35], v[178:181], v[194:197], v[32:35]
	v_mfma_f32_16x16x32_bf16 v[20:23], v[170:173], v[202:205], v[20:23]
	v_mfma_f32_16x16x32_bf16 v[16:19], v[178:181], v[202:205], v[16:19]
	v_mfma_f32_16x16x32_bf16 v[4:7], v[170:173], v[210:213], v[4:7]
	v_mfma_f32_16x16x32_bf16 v[0:3], v[178:181], v[210:213], v[0:3]
	s_setprio 0
	s_barrier
	s_add_i32 s50, 0, 0x18000
	s_add_i32 s51, 0, 0x1c000
	v_add_u32_e32 v162, s50, v149
	v_add_u32_e32 v178, s51, v149
	ds_read_b128 v[144:147], v162
	ds_read_b128 v[154:157], v162 offset:1024
	ds_read_b128 v[158:161], v162 offset:2048
	ds_read_b128 v[162:165], v162 offset:3072
	ds_read_b128 v[166:169], v178
	ds_read_b128 v[170:173], v178 offset:1024
	ds_read_b128 v[174:177], v178 offset:2048
	ds_read_b128 v[178:181], v178 offset:3072
	s_add_u32 s26, s26, 0x80000
	s_addc_u32 s27, s27, 0
	s_mov_b32 m0, s36
	v_lshl_add_u64 v[222:223], s[26:27], 0, v[128:129]
	ds_read_b128 v[182:185], v153 offset:32768
	ds_read_b128 v[186:189], v153 offset:33792
	ds_read_b128 v[190:193], v153 offset:34816
	ds_read_b128 v[194:197], v153 offset:35840
	ds_read_b128 v[198:201], v153 offset:36864
	ds_read_b128 v[202:205], v153 offset:37888
	ds_read_b128 v[206:209], v153 offset:38912
	ds_read_b128 v[210:213], v153 offset:39936
	global_load_lds_dwordx4 v[222:223], off
	v_lshl_add_u64 v[222:223], s[26:27], 0, v[132:133]
	s_mov_b32 m0, s37
	s_nop 0
	global_load_lds_dwordx4 v[222:223], off
	s_waitcnt vmcnt(8)
	s_waitcnt lgkmcnt(0)
	s_barrier
	s_setprio 1
	s_waitcnt lgkmcnt(0)
	v_mfma_f32_16x16x32_bf16 v[124:127], v[144:147], v[182:185], v[124:127]
	v_mfma_f32_16x16x32_bf16 v[120:123], v[158:161], v[182:185], v[120:123]
	v_mfma_f32_16x16x32_bf16 v[108:111], v[144:147], v[190:193], v[108:111]
	v_mfma_f32_16x16x32_bf16 v[104:107], v[158:161], v[190:193], v[104:107]
	v_mfma_f32_16x16x32_bf16 v[92:95], v[144:147], v[198:201], v[92:95]
	v_mfma_f32_16x16x32_bf16 v[88:91], v[158:161], v[198:201], v[88:91]
	v_mfma_f32_16x16x32_bf16 v[76:79], v[144:147], v[206:209], v[76:79]
	v_mfma_f32_16x16x32_bf16 v[72:75], v[158:161], v[206:209], v[72:75]
	v_mfma_f32_16x16x32_bf16 v[124:127], v[154:157], v[186:189], v[124:127]
	v_mfma_f32_16x16x32_bf16 v[120:123], v[162:165], v[186:189], v[120:123]
	v_mfma_f32_16x16x32_bf16 v[108:111], v[154:157], v[194:197], v[108:111]
	v_mfma_f32_16x16x32_bf16 v[104:107], v[162:165], v[194:197], v[104:107]
	v_mfma_f32_16x16x32_bf16 v[92:95], v[154:157], v[202:205], v[92:95]
	v_mfma_f32_16x16x32_bf16 v[88:91], v[162:165], v[202:205], v[88:91]
	v_mfma_f32_16x16x32_bf16 v[76:79], v[154:157], v[210:213], v[76:79]
	v_mfma_f32_16x16x32_bf16 v[72:75], v[162:165], v[210:213], v[72:75]
	s_setprio 0
	s_setprio 1
	v_mfma_f32_16x16x32_bf16 v[116:119], v[166:169], v[182:185], v[116:119]
	v_mfma_f32_16x16x32_bf16 v[112:115], v[174:177], v[182:185], v[112:115]
	v_mfma_f32_16x16x32_bf16 v[100:103], v[166:169], v[190:193], v[100:103]
	v_mfma_f32_16x16x32_bf16 v[96:99], v[174:177], v[190:193], v[96:99]
	v_mfma_f32_16x16x32_bf16 v[84:87], v[166:169], v[198:201], v[84:87]
	v_mfma_f32_16x16x32_bf16 v[80:83], v[174:177], v[198:201], v[80:83]
	v_mfma_f32_16x16x32_bf16 v[68:71], v[166:169], v[206:209], v[68:71]
	v_mfma_f32_16x16x32_bf16 v[64:67], v[174:177], v[206:209], v[64:67]
	v_mfma_f32_16x16x32_bf16 v[116:119], v[170:173], v[186:189], v[116:119]
	v_mfma_f32_16x16x32_bf16 v[112:115], v[178:181], v[186:189], v[112:115]
	v_mfma_f32_16x16x32_bf16 v[100:103], v[170:173], v[194:197], v[100:103]
	v_mfma_f32_16x16x32_bf16 v[96:99], v[178:181], v[194:197], v[96:99]
	v_mfma_f32_16x16x32_bf16 v[84:87], v[170:173], v[202:205], v[84:87]
	v_mfma_f32_16x16x32_bf16 v[80:83], v[178:181], v[202:205], v[80:83]
	v_mfma_f32_16x16x32_bf16 v[68:71], v[170:173], v[210:213], v[68:71]
	v_mfma_f32_16x16x32_bf16 v[64:67], v[178:181], v[210:213], v[64:67]
	s_setprio 0
	s_barrier
; #define PG8_STAGE(bufoff, gbase, voff) do { _Pragma("unroll") for (int _i = 0; _i < 2; ++_i) \
;         __builtin_amdgcn_global_load_lds((const unsigned*)((const char*)(gbase) + (voff)[_i]), (PG8_LAS unsigned*)(lds + (bufoff) + ldsw + _i * 8192), 16, 0, 0); } while (0)
; #define PG8_LDA(dst, b, h) do { _Pragma("unroll") for (int m = 0; m < 4; ++m) _Pragma("unroll") for (int k = 0; k < 2; ++k) dst[m][k] = *(const PG8_LAS bf16x8*)(lds + PG8_SA(b, h) + aoff + m * 2048 + k * 1024); } while (0)
; #define PG8_MMA(ai, bj, At, Bt) do { __builtin_amdgcn_s_setprio(1); _Pragma("unroll") for (int m = 0; m < 4; ++m) _Pragma("unroll") for (int n = 0; n < 2; ++n) _Pragma("unroll") for (int k = 0; k < 2; ++k) \
;         acc[ai][bj][m][n] = __builtin_amdgcn_mfma_f32_16x16x32_bf16(Bt[n][k], At[m][k], acc[ai][bj][m][n], 0, 0, 0); __builtin_amdgcn_s_setprio(0); } while (0)
; #define PG8_WAIT_V(n) asm volatile("s_waitcnt vmcnt(" #n ")" ::: "memory")
; #define PG8_WAIT_L(n) asm volatile("s_waitcnt lgkmcnt(" #n ")" ::: "memory")
; #define PG8_BAR __builtin_amdgcn_s_barrier()
; #define PG8_SCHED __builtin_amdgcn_sched_barrier(0)
; template <class Epi, class Sched, bool ALIGN_EPI = false, bool SP2 = false>
; __device__ __forceinline__ void gemm_phase(PG8_LAS unsigned char* lds, const Gemm g, const Sched& S, const Epi& E, const int wave_in) {
;     ...
;         for (int t = 0; t < nt; t += 2) {
;             const bool last = (t == nt - 2);
;     ...
;             PG8_LDA(At, 1, 1); PG8_STAGE(PG8_SB(1, 0), b3, voffB); PG8_STAGE(PG8_SB(1, 1), b3 + hstepB, voffB); PG8_STAGE(PG8_SA(1, 0), a3, voffA);
;             PG8_WAIT_V(8); PG8_WAIT_L(0); PG8_BAR; PG8_MMA(1, 0, At, B0); PG8_MMA(1, 1, At, B1); PG8_BAR; PG8_SCHED;
	s_add_i32 s26, s50, s34
	v_lshl_add_u64 v[214:215], v[214:215], 0, s[8:9]
	s_mov_b32 m0, s26
	ds_read_b128 v[182:185], v153 offset:49152
	ds_read_b128 v[186:189], v153 offset:50176
	ds_read_b128 v[190:193], v153 offset:51200
	ds_read_b128 v[194:197], v153 offset:52224
	ds_read_b128 v[198:201], v153 offset:53248
	ds_read_b128 v[202:205], v153 offset:54272
	ds_read_b128 v[206:209], v153 offset:55296
	ds_read_b128 v[210:213], v153 offset:56320
	global_load_lds_dwordx4 v[214:215], off
	s_add_i32 m0, s26, 0x2000
	s_add_u32 s24, s24, 0x80080
	v_lshl_add_u64 v[214:215], v[216:217], 0, s[8:9]
	s_addc_u32 s25, s25, 0
	s_add_i32 s26, s51, s34
	global_load_lds_dwordx4 v[214:215], off
	v_lshl_add_u64 v[214:215], s[24:25], 0, v[130:131]
	s_mov_b32 m0, s26
	s_nop 0
	global_load_lds_dwordx4 v[214:215], off
	v_lshl_add_u64 v[214:215], s[24:25], 0, v[134:135]
	s_add_i32 m0, s26, 0x2000
	s_nop 0
	global_load_lds_dwordx4 v[214:215], off
	v_lshl_add_u64 v[214:215], v[218:219], 0, s[8:9]
	s_mov_b32 m0, s39
	s_nop 0
	global_load_lds_dwordx4 v[214:215], off
	v_lshl_add_u64 v[214:215], v[220:221], 0, s[8:9]
	s_mov_b32 m0, s40
	s_nop 0
	global_load_lds_dwordx4 v[214:215], off
	s_waitcnt vmcnt(8)
	s_waitcnt lgkmcnt(0)
	s_barrier
	s_setprio 1
	s_waitcnt lgkmcnt(0)
	v_mfma_f32_16x16x32_bf16 v[60:63], v[144:147], v[182:185], v[60:63]
	v_mfma_f32_16x16x32_bf16 v[56:59], v[158:161], v[182:185], v[56:59]
	v_mfma_f32_16x16x32_bf16 v[44:47], v[144:147], v[190:193], v[44:47]
	v_mfma_f32_16x16x32_bf16 v[40:43], v[158:161], v[190:193], v[40:43]
	v_mfma_f32_16x16x32_bf16 v[28:31], v[144:147], v[198:201], v[28:31]
	v_mfma_f32_16x16x32_bf16 v[24:27], v[158:161], v[198:201], v[24:27]
	v_mfma_f32_16x16x32_bf16 v[12:15], v[144:147], v[206:209], v[12:15]
	v_mfma_f32_16x16x32_bf16 v[8:11], v[158:161], v[206:209], v[8:11]
	v_mfma_f32_16x16x32_bf16 v[60:63], v[154:157], v[186:189], v[60:63]
	v_mfma_f32_16x16x32_bf16 v[56:59], v[162:165], v[186:189], v[56:59]
	v_mfma_f32_16x16x32_bf16 v[44:47], v[154:157], v[194:197], v[44:47]
	v_mfma_f32_16x16x32_bf16 v[40:43], v[162:165], v[194:197], v[40:43]
	v_mfma_f32_16x16x32_bf16 v[28:31], v[154:157], v[202:205], v[28:31]
	v_mfma_f32_16x16x32_bf16 v[24:27], v[162:165], v[202:205], v[24:27]
	v_mfma_f32_16x16x32_bf16 v[12:15], v[154:157], v[210:213], v[12:15]
	v_mfma_f32_16x16x32_bf16 v[8:11], v[162:165], v[210:213], v[8:11]
	s_setprio 0
	s_setprio 1
	v_mfma_f32_16x16x32_bf16 v[52:55], v[166:169], v[182:185], v[52:55]
	v_mfma_f32_16x16x32_bf16 v[48:51], v[174:177], v[182:185], v[48:51]
	v_mfma_f32_16x16x32_bf16 v[36:39], v[166:169], v[190:193], v[36:39]
	v_mfma_f32_16x16x32_bf16 v[32:35], v[174:177], v[190:193], v[32:35]
	v_mfma_f32_16x16x32_bf16 v[20:23], v[166:169], v[198:201], v[20:23]
	v_mfma_f32_16x16x32_bf16 v[16:19], v[174:177], v[198:201], v[16:19]
	v_mfma_f32_16x16x32_bf16 v[4:7], v[166:169], v[206:209], v[4:7]
	v_mfma_f32_16x16x32_bf16 v[0:3], v[174:177], v[206:209], v[0:3]
	v_mfma_f32_16x16x32_bf16 v[52:55], v[170:173], v[186:189], v[52:55]
	v_mfma_f32_16x16x32_bf16 v[48:51], v[178:181], v[186:189], v[48:51]
	v_mfma_f32_16x16x32_bf16 v[36:39], v[170:173], v[194:197], v[36:39]
	v_mfma_f32_16x16x32_bf16 v[32:35], v[178:181], v[194:197], v[32:35]
	v_mfma_f32_16x16x32_bf16 v[20:23], v[170:173], v[202:205], v[20:23]
	v_mfma_f32_16x16x32_bf16 v[16:19], v[178:181], v[202:205], v[16:19]
	v_mfma_f32_16x16x32_bf16 v[4:7], v[170:173], v[210:213], v[4:7]
	v_mfma_f32_16x16x32_bf16 v[0:3], v[178:181], v[210:213], v[0:3]
	s_setprio 0
	s_add_i32 s49, s49, 2
	s_add_u32 s22, s22, 0x100
	s_addc_u32 s23, s23, 0
	s_add_u32 s47, s47, 0x100
	s_addc_u32 s48, s48, 0
	s_cmp_gt_u32 s49, 29
	s_barrier
	s_cbranch_scc0 .LBB0_158
	s_and_b64 vcc, exec, s[10:11]
	s_cbranch_vccz .LBB0_161
	s_barrier

; #define PG8_STAGE(bufoff, gbase, voff) do { _Pragma("unroll") for (int _i = 0; _i < 2; ++_i) \
;         __builtin_amdgcn_global_load_lds((const unsigned*)((const char*)(gbase) + (voff)[_i]), (PG8_LAS unsigned*)(lds + (bufoff) + ldsw + _i * 8192), 16, 0, 0); } while (0)
; #define PG8_LDA(dst, b, h) do { _Pragma("unroll") for (int m = 0; m < 4; ++m) _Pragma("unroll") for (int k = 0; k < 2; ++k) dst[m][k] = *(const PG8_LAS bf16x8*)(lds + PG8_SA(b, h) + aoff + m * 2048 + k * 1024); } while (0)
; #define PG8_LDB(dst, b, h) do { _Pragma("unroll") for (int n = 0; n < 2; ++n) _Pragma("unroll") for (int k = 0; k < 2; ++k) dst[n][k] = *(const PG8_LAS bf16x8*)(lds + PG8_SB(b, h) + boff + n * 2048 + k * 1024); } while (0)
; #define PG8_MMA(ai, bj, At, Bt) do { __builtin_amdgcn_s_setprio(1); _Pragma("unroll") for (int m = 0; m < 4; ++m) _Pragma("unroll") for (int n = 0; n < 2; ++n) _Pragma("unroll") for (int k = 0; k < 2; ++k) \
;         acc[ai][bj][m][n] = __builtin_amdgcn_mfma_f32_16x16x32_bf16(Bt[n][k], At[m][k], acc[ai][bj][m][n], 0, 0, 0); __builtin_amdgcn_s_setprio(0); } while (0)
; #define PG8_WAIT_V(n) asm volatile("s_waitcnt vmcnt(" #n ")" ::: "memory")
; #define PG8_WAIT_L(n) asm volatile("s_waitcnt lgkmcnt(" #n ")" ::: "memory")
; #define PG8_BAR __builtin_amdgcn_s_barrier()
; template <class Epi, class Sched, bool ALIGN_EPI = false, bool SP2 = false>
; __device__ __forceinline__ void gemm_phase(PG8_LAS unsigned char* lds, const Gemm g, const Sched& S, const Epi& E, const int wave_in) {
;     ...
;         for (int t = 0; t < nt; t += 2) {
;             const bool last = (t == nt - 2);
;             const char* a1 = cA + (size_t)(t + 1) * kstep;
;             const char* a2 = last ? nA : cA + (size_t)(t + 2) * kstep; const char* b2 = last ? nB : cB + (size_t)(t + 2) * kstep;
;             const char* a3 = a2 + kstep; const char* b3 = b2 + kstep;
;             if (last && has_next) S.a_ready(nxt);
;             if constexpr (SP2) {
;             PG8_LDB(B0, 0, 0); PG8_LDB(B1, 0, 1); PG8_SCHED; PG8_LDA(At, 0, 0); PG8_STAGE(PG8_SA(1, 1), a1 + hstepA, voffA);
;             PG8_WAIT_V(8); PG8_WAIT_L(0); PG8_BAR; PG8_MMA(0, 0, At, B0); PG8_MMA(0, 1, At, B1); PG8_BAR; PG8_SCHED;
;             PG8_LDA(At, 0, 1); PG8_STAGE(PG8_SB(0, 0), b2, voffB); PG8_STAGE(PG8_SB(0, 1), b2 + hstepB, voffB); PG8_STAGE(PG8_SA(0, 0), a2, voffA);
.LBB0_479:
	ds_read_b128 v[44:47], v189
	ds_read_b128 v[48:51], v189 offset:1024
	ds_read_b128 v[52:55], v189 offset:2048
	ds_read_b128 v[56:59], v189 offset:3072
	ds_read_b128 v[60:63], v197
	ds_read_b128 v[64:67], v197 offset:1024
	ds_read_b128 v[80:83], v197 offset:2048
	ds_read_b128 v[84:87], v197 offset:3072
	s_add_u32 s48, s46, 0xfff80080
	s_addc_u32 s49, s47, -1
	s_cmp_eq_u32 s74, 28
	s_cselect_b32 s51, s1, s49
	s_cselect_b32 s50, s13, s48
	s_cselect_b32 s49, s39, s73
	s_cselect_b32 s48, s41, s72
	v_lshl_add_u64 v[224:225], s[46:47], 0, v[206:207]
	s_add_i32 m0, s57, 0xc000
	ds_read_b128 v[88:91], v199
	ds_read_b128 v[92:95], v199 offset:1024
	ds_read_b128 v[96:99], v199 offset:2048
	ds_read_b128 v[100:103], v199 offset:3072
	ds_read_b128 v[176:179], v199 offset:4096
	ds_read_b128 v[212:215], v199 offset:5120
	ds_read_b128 v[216:219], v199 offset:6144
	ds_read_b128 v[220:223], v199 offset:7168
	global_load_lds_dwordx4 v[224:225], off
	v_lshl_add_u64 v[224:225], s[46:47], 0, v[208:209]
	s_add_i32 m0, s57, 0xe000
	s_nop 0
	global_load_lds_dwordx4 v[224:225], off
	s_waitcnt vmcnt(8)
	s_waitcnt lgkmcnt(0)
	s_barrier
	s_setprio 1
	s_waitcnt lgkmcnt(0)
	v_mfma_f32_16x16x32_bf16 v[172:175], v[44:47], v[88:91], v[172:175]
	v_mfma_f32_16x16x32_bf16 v[164:167], v[52:55], v[88:91], v[164:167]
	v_mfma_f32_16x16x32_bf16 v[156:159], v[44:47], v[96:99], v[156:159]
	v_mfma_f32_16x16x32_bf16 v[148:151], v[52:55], v[96:99], v[148:151]
	v_mfma_f32_16x16x32_bf16 v[140:143], v[44:47], v[176:179], v[140:143]
	v_mfma_f32_16x16x32_bf16 v[132:135], v[52:55], v[176:179], v[132:135]
	v_mfma_f32_16x16x32_bf16 v[124:127], v[44:47], v[216:219], v[124:127]
	v_mfma_f32_16x16x32_bf16 v[120:123], v[52:55], v[216:219], v[120:123]
	v_mfma_f32_16x16x32_bf16 v[172:175], v[48:51], v[92:95], v[172:175]
	v_mfma_f32_16x16x32_bf16 v[164:167], v[56:59], v[92:95], v[164:167]
	v_mfma_f32_16x16x32_bf16 v[156:159], v[48:51], v[100:103], v[156:159]
	v_mfma_f32_16x16x32_bf16 v[148:151], v[56:59], v[100:103], v[148:151]
	v_mfma_f32_16x16x32_bf16 v[140:143], v[48:51], v[212:215], v[140:143]
	v_mfma_f32_16x16x32_bf16 v[132:135], v[56:59], v[212:215], v[132:135]
	v_mfma_f32_16x16x32_bf16 v[124:127], v[48:51], v[220:223], v[124:127]
	v_mfma_f32_16x16x32_bf16 v[120:123], v[56:59], v[220:223], v[120:123]
	s_setprio 0
	s_setprio 1
	v_mfma_f32_16x16x32_bf16 v[168:171], v[60:63], v[88:91], v[168:171]
	v_mfma_f32_16x16x32_bf16 v[88:91], v[80:83], v[88:91], v[160:163]
	v_mfma_f32_16x16x32_bf16 v[168:171], v[64:67], v[92:95], v[168:171]
	v_mfma_f32_16x16x32_bf16 v[88:91], v[84:87], v[92:95], v[88:91]
	v_mfma_f32_16x16x32_bf16 v[92:95], v[60:63], v[96:99], v[152:155]
	v_mfma_f32_16x16x32_bf16 v[96:99], v[80:83], v[96:99], v[144:147]
	v_mfma_f32_16x16x32_bf16 v[128:131], v[80:83], v[176:179], v[128:131]
	v_mfma_f32_16x16x32_bf16 v[116:119], v[60:63], v[216:219], v[116:119]
	v_mfma_f32_16x16x32_bf16 v[112:115], v[80:83], v[216:219], v[112:115]
	v_mfma_f32_16x16x32_bf16 v[92:95], v[64:67], v[100:103], v[92:95]
	v_mfma_f32_16x16x32_bf16 v[96:99], v[84:87], v[100:103], v[96:99]
	v_mfma_f32_16x16x32_bf16 v[100:103], v[60:63], v[176:179], v[136:139]
	v_mfma_f32_16x16x32_bf16 v[128:131], v[84:87], v[212:215], v[128:131]
	v_mfma_f32_16x16x32_bf16 v[116:119], v[64:67], v[220:223], v[116:119]
	v_mfma_f32_16x16x32_bf16 v[112:115], v[84:87], v[220:223], v[112:115]
	v_mfma_f32_16x16x32_bf16 v[100:103], v[64:67], v[212:215], v[100:103]
	s_setprio 0
	s_barrier
	s_add_i32 s75, s68, s56
	v_lshl_add_u64 v[232:233], s[48:49], 0, v[182:183]
	s_mov_b32 m0, s75
	ds_read_b128 v[136:139], v199 offset:16384
	ds_read_b128 v[144:147], v199 offset:17408
	ds_read_b128 v[152:155], v199 offset:18432
	ds_read_b128 v[160:163], v199 offset:19456
	ds_read_b128 v[176:179], v199 offset:20480
	ds_read_b128 v[212:215], v199 offset:21504
	ds_read_b128 v[216:219], v199 offset:22528
	ds_read_b128 v[220:223], v199 offset:23552
	global_load_lds_dwordx4 v[232:233], off
	s_add_i32 m0, s75, 0x2000
	s_add_u32 s76, s48, 0x80000
	v_lshl_add_u64 v[234:235], s[48:49], 0, v[186:187]
	s_addc_u32 s77, s49, 0
	s_add_i32 s75, s69, s56
	global_load_lds_dwordx4 v[234:235], off
	v_lshl_add_u64 v[224:225], s[76:77], 0, v[182:183]
	s_mov_b32 m0, s75
	v_lshl_add_u64 v[236:237], s[50:51], 0, v[180:181]
	global_load_lds_dwordx4 v[224:225], off
	v_lshl_add_u64 v[224:225], s[76:77], 0, v[186:187]
	s_add_i32 m0, s75, 0x2000
	v_lshl_add_u64 v[238:239], s[50:51], 0, v[184:185]
	global_load_lds_dwordx4 v[224:225], off
	s_mov_b32 m0, s57
	s_nop 0
	global_load_lds_dwordx4 v[236:237], off
	s_mov_b32 m0, s58
	s_nop 0
	global_load_lds_dwordx4 v[238:239], off
	s_waitcnt vmcnt(8)
	s_waitcnt lgkmcnt(0)
	s_barrier
; #define PG8_STAGE(bufoff, gbase, voff) do { _Pragma("unroll") for (int _i = 0; _i < 2; ++_i) \
;         __builtin_amdgcn_global_load_lds((const unsigned*)((const char*)(gbase) + (voff)[_i]), (PG8_LAS unsigned*)(lds + (bufoff) + ldsw + _i * 8192), 16, 0, 0); } while (0)
; #define PG8_LDA(dst, b, h) do { _Pragma("unroll") for (int m = 0; m < 4; ++m) _Pragma("unroll") for (int k = 0; k < 2; ++k) dst[m][k] = *(const PG8_LAS bf16x8*)(lds + PG8_SA(b, h) + aoff + m * 2048 + k * 1024); } while (0)
; #define PG8_LDB(dst, b, h) do { _Pragma("unroll") for (int n = 0; n < 2; ++n) _Pragma("unroll") for (int k = 0; k < 2; ++k) dst[n][k] = *(const PG8_LAS bf16x8*)(lds + PG8_SB(b, h) + boff + n * 2048 + k * 1024); } while (0)
; #define PG8_MMA(ai, bj, At, Bt) do { __builtin_amdgcn_s_setprio(1); _Pragma("unroll") for (int m = 0; m < 4; ++m) _Pragma("unroll") for (int n = 0; n < 2; ++n) _Pragma("unroll") for (int k = 0; k < 2; ++k) \
;         acc[ai][bj][m][n] = __builtin_amdgcn_mfma_f32_16x16x32_bf16(Bt[n][k], At[m][k], acc[ai][bj][m][n], 0, 0, 0); __builtin_amdgcn_s_setprio(0); } while (0)
; #define PG8_WAIT_V(n) asm volatile("s_waitcnt vmcnt(" #n ")" ::: "memory")
; #define PG8_WAIT_L(n) asm volatile("s_waitcnt lgkmcnt(" #n ")" ::: "memory")
; #define PG8_BAR __builtin_amdgcn_s_barrier()
; #define PG8_SCHED __builtin_amdgcn_sched_barrier(0)
; template <class Epi, class Sched, bool ALIGN_EPI = false, bool SP2 = false>
; __device__ __forceinline__ void gemm_phase(PG8_LAS unsigned char* lds, const Gemm g, const Sched& S, const Epi& E, const int wave_in) {
;     ...
;             PG8_WAIT_V(8); PG8_WAIT_L(0); PG8_BAR; PG8_MMA(1, 0, At, B0); PG8_MMA(1, 1, At, B1); PG8_BAR; PG8_SCHED;
;             PG8_LDB(B0, 1, 0); PG8_LDB(B1, 1, 1); PG8_SCHED; PG8_LDA(At, 1, 0); PG8_STAGE(PG8_SA(0, 1), a2 + hstepA, voffA);
;             PG8_WAIT_V(8); PG8_WAIT_L(0); PG8_BAR; PG8_MMA(0, 0, At, B0); PG8_MMA(0, 1, At, B1); PG8_BAR; PG8_SCHED;
	s_setprio 1
	s_waitcnt lgkmcnt(0)
	v_mfma_f32_16x16x32_bf16 v[108:111], v[44:47], v[136:139], v[108:111]
	v_mfma_f32_16x16x32_bf16 v[76:79], v[52:55], v[136:139], v[76:79]
	v_mfma_f32_16x16x32_bf16 v[68:71], v[44:47], v[152:155], v[68:71]
	v_mfma_f32_16x16x32_bf16 v[36:39], v[52:55], v[152:155], v[36:39]
	v_mfma_f32_16x16x32_bf16 v[28:31], v[44:47], v[176:179], v[28:31]
	v_mfma_f32_16x16x32_bf16 v[20:23], v[52:55], v[176:179], v[20:23]
	v_mfma_f32_16x16x32_bf16 v[12:15], v[44:47], v[216:219], v[12:15]
	v_mfma_f32_16x16x32_bf16 v[8:11], v[52:55], v[216:219], v[8:11]
	v_mfma_f32_16x16x32_bf16 v[108:111], v[48:51], v[144:147], v[108:111]
	v_mfma_f32_16x16x32_bf16 v[76:79], v[56:59], v[144:147], v[76:79]
	v_mfma_f32_16x16x32_bf16 v[68:71], v[48:51], v[160:163], v[68:71]
	v_mfma_f32_16x16x32_bf16 v[36:39], v[56:59], v[160:163], v[36:39]
	v_mfma_f32_16x16x32_bf16 v[28:31], v[48:51], v[212:215], v[28:31]
	v_mfma_f32_16x16x32_bf16 v[20:23], v[56:59], v[212:215], v[20:23]
	v_mfma_f32_16x16x32_bf16 v[12:15], v[48:51], v[220:223], v[12:15]
	v_mfma_f32_16x16x32_bf16 v[8:11], v[56:59], v[220:223], v[8:11]
	s_setprio 0
	s_setprio 1
	v_mfma_f32_16x16x32_bf16 v[40:43], v[60:63], v[152:155], v[40:43]
	v_mfma_f32_16x16x32_bf16 v[32:35], v[80:83], v[152:155], v[32:35]
	v_mfma_f32_16x16x32_bf16 v[24:27], v[60:63], v[176:179], v[24:27]
	v_mfma_f32_16x16x32_bf16 v[16:19], v[80:83], v[176:179], v[16:19]
	v_mfma_f32_16x16x32_bf16 v[4:7], v[60:63], v[216:219], v[4:7]
	v_mfma_f32_16x16x32_bf16 v[0:3], v[80:83], v[216:219], v[0:3]
	v_mfma_f32_16x16x32_bf16 v[44:47], v[60:63], v[136:139], v[104:107]
	v_mfma_f32_16x16x32_bf16 v[48:51], v[80:83], v[136:139], v[72:75]
	v_mfma_f32_16x16x32_bf16 v[40:43], v[64:67], v[160:163], v[40:43]
	v_mfma_f32_16x16x32_bf16 v[32:35], v[84:87], v[160:163], v[32:35]
	v_mfma_f32_16x16x32_bf16 v[24:27], v[64:67], v[212:215], v[24:27]
	v_mfma_f32_16x16x32_bf16 v[16:19], v[84:87], v[212:215], v[16:19]
	v_mfma_f32_16x16x32_bf16 v[4:7], v[64:67], v[220:223], v[4:7]
	v_mfma_f32_16x16x32_bf16 v[0:3], v[84:87], v[220:223], v[0:3]
	v_mfma_f32_16x16x32_bf16 v[44:47], v[64:67], v[144:147], v[44:47]
	v_mfma_f32_16x16x32_bf16 v[48:51], v[84:87], v[144:147], v[48:51]
	s_setprio 0
	s_barrier
	s_add_i32 s75, 0, 0x18000
	s_add_i32 s76, 0, 0x1c000
	v_add_u32_e32 v64, s75, v195
	v_add_u32_e32 v72, s76, v195
	ds_read_b128 v[52:55], v64
	ds_read_b128 v[56:59], v64 offset:1024
	ds_read_b128 v[60:63], v64 offset:2048
	ds_read_b128 v[64:67], v64 offset:3072
	ds_read_b128 v[80:83], v72
	ds_read_b128 v[84:87], v72 offset:1024
	ds_read_b128 v[176:179], v72 offset:2048
	ds_read_b128 v[212:215], v72 offset:3072
	s_add_u32 s50, s50, 0x80000
	s_addc_u32 s51, s51, 0
	s_mov_b32 m0, s59
	v_lshl_add_u64 v[152:153], s[50:51], 0, v[180:181]
	ds_read_b128 v[72:75], v199 offset:32768
	ds_read_b128 v[104:107], v199 offset:33792
	ds_read_b128 v[136:139], v199 offset:34816
	ds_read_b128 v[144:147], v199 offset:35840
	ds_read_b128 v[216:219], v199 offset:36864
	ds_read_b128 v[220:223], v199 offset:37888
	ds_read_b128 v[224:227], v199 offset:38912
	ds_read_b128 v[228:231], v199 offset:39936
	global_load_lds_dwordx4 v[152:153], off
	v_lshl_add_u64 v[152:153], s[50:51], 0, v[184:185]
	s_mov_b32 m0, s60
	s_nop 0
	global_load_lds_dwordx4 v[152:153], off
	s_waitcnt vmcnt(8)
	s_waitcnt lgkmcnt(0)
	s_barrier
	s_setprio 1
	s_waitcnt lgkmcnt(0)
	v_mfma_f32_16x16x32_bf16 v[152:155], v[52:55], v[72:75], v[172:175]
	v_mfma_f32_16x16x32_bf16 v[172:175], v[56:59], v[104:107], v[152:155]
	v_mfma_f32_16x16x32_bf16 v[152:155], v[60:63], v[72:75], v[164:167]
	v_mfma_f32_16x16x32_bf16 v[164:167], v[64:67], v[104:107], v[152:155]
	v_mfma_f32_16x16x32_bf16 v[152:155], v[52:55], v[136:139], v[156:159]
	v_mfma_f32_16x16x32_bf16 v[148:151], v[60:63], v[136:139], v[148:151]
	v_mfma_f32_16x16x32_bf16 v[140:143], v[52:55], v[216:219], v[140:143]
	v_mfma_f32_16x16x32_bf16 v[132:135], v[60:63], v[216:219], v[132:135]
	v_mfma_f32_16x16x32_bf16 v[124:127], v[52:55], v[224:227], v[124:127]
	v_mfma_f32_16x16x32_bf16 v[120:123], v[60:63], v[224:227], v[120:123]
	v_mfma_f32_16x16x32_bf16 v[156:159], v[56:59], v[144:147], v[152:155]
	v_mfma_f32_16x16x32_bf16 v[148:151], v[64:67], v[144:147], v[148:151]
	v_mfma_f32_16x16x32_bf16 v[140:143], v[56:59], v[220:223], v[140:143]
	v_mfma_f32_16x16x32_bf16 v[132:135], v[64:67], v[220:223], v[132:135]
	v_mfma_f32_16x16x32_bf16 v[124:127], v[56:59], v[228:231], v[124:127]
	v_mfma_f32_16x16x32_bf16 v[120:123], v[64:67], v[228:231], v[120:123]
	s_setprio 0
	s_setprio 1
	v_mfma_f32_16x16x32_bf16 v[152:155], v[80:83], v[72:75], v[168:171]
	v_mfma_f32_16x16x32_bf16 v[72:75], v[176:179], v[72:75], v[88:91]
	v_mfma_f32_16x16x32_bf16 v[160:163], v[212:215], v[104:107], v[72:75]
	v_mfma_f32_16x16x32_bf16 v[72:75], v[80:83], v[136:139], v[92:95]
	v_mfma_f32_16x16x32_bf16 v[168:171], v[84:87], v[104:107], v[152:155]
	v_mfma_f32_16x16x32_bf16 v[152:155], v[84:87], v[144:147], v[72:75]
	v_mfma_f32_16x16x32_bf16 v[72:75], v[176:179], v[136:139], v[96:99]
	v_mfma_f32_16x16x32_bf16 v[144:147], v[212:215], v[144:147], v[72:75]
	v_mfma_f32_16x16x32_bf16 v[72:75], v[80:83], v[216:219], v[100:103]
	v_mfma_f32_16x16x32_bf16 v[136:139], v[84:87], v[220:223], v[72:75]
	v_mfma_f32_16x16x32_bf16 v[72:75], v[176:179], v[216:219], v[128:131]
	v_mfma_f32_16x16x32_bf16 v[128:131], v[212:215], v[220:223], v[72:75]
	v_mfma_f32_16x16x32_bf16 v[72:75], v[80:83], v[224:227], v[116:119]
	v_mfma_f32_16x16x32_bf16 v[116:119], v[84:87], v[228:231], v[72:75]
	v_mfma_f32_16x16x32_bf16 v[72:75], v[176:179], v[224:227], v[112:115]
	v_mfma_f32_16x16x32_bf16 v[112:115], v[212:215], v[228:231], v[72:75]
	s_setprio 0
	s_barrier
; #define PG8_STAGE(bufoff, gbase, voff) do { _Pragma("unroll") for (int _i = 0; _i < 2; ++_i) \
;         __builtin_amdgcn_global_load_lds((const unsigned*)((const char*)(gbase) + (voff)[_i]), (PG8_LAS unsigned*)(lds + (bufoff) + ldsw + _i * 8192), 16, 0, 0); } while (0)
; #define PG8_LDA(dst, b, h) do { _Pragma("unroll") for (int m = 0; m < 4; ++m) _Pragma("unroll") for (int k = 0; k < 2; ++k) dst[m][k] = *(const PG8_LAS bf16x8*)(lds + PG8_SA(b, h) + aoff + m * 2048 + k * 1024); } while (0)
; #define PG8_MMA(ai, bj, At, Bt) do { __builtin_amdgcn_s_setprio(1); _Pragma("unroll") for (int m = 0; m < 4; ++m) _Pragma("unroll") for (int n = 0; n < 2; ++n) _Pragma("unroll") for (int k = 0; k < 2; ++k) \
;         acc[ai][bj][m][n] = __builtin_amdgcn_mfma_f32_16x16x32_bf16(Bt[n][k], At[m][k], acc[ai][bj][m][n], 0, 0, 0); __builtin_amdgcn_s_setprio(0); } while (0)
; #define PG8_WAIT_V(n) asm volatile("s_waitcnt vmcnt(" #n ")" ::: "memory")
; #define PG8_WAIT_L(n) asm volatile("s_waitcnt lgkmcnt(" #n ")" ::: "memory")
; #define PG8_BAR __builtin_amdgcn_s_barrier()
; #define PG8_SCHED __builtin_amdgcn_sched_barrier(0)
; template <class Epi, class Sched, bool ALIGN_EPI = false, bool SP2 = false>
; __device__ __forceinline__ void gemm_phase(PG8_LAS unsigned char* lds, const Gemm g, const Sched& S, const Epi& E, const int wave_in) {
;     ...
;         for (int t = 0; t < nt; t += 2) {
;             const bool last = (t == nt - 2);
;     ...
;             PG8_LDA(At, 1, 1); PG8_STAGE(PG8_SB(1, 0), b3, voffB); PG8_STAGE(PG8_SB(1, 1), b3 + hstepB, voffB); PG8_STAGE(PG8_SA(1, 0), a3, voffA);
;             PG8_WAIT_V(8); PG8_WAIT_L(0); PG8_BAR; PG8_MMA(1, 0, At, B0); PG8_MMA(1, 1, At, B1); PG8_BAR; PG8_SCHED;
	s_add_i32 s50, s75, s56
	v_lshl_add_u64 v[104:105], v[232:233], 0, s[22:23]
	s_mov_b32 m0, s50
	s_nop 1
	ds_read_b128 v[72:75], v199 offset:49152
	ds_read_b128 v[88:91], v199 offset:50176
	ds_read_b128 v[92:95], v199 offset:51200
	ds_read_b128 v[96:99], v199 offset:52224
	ds_read_b128 v[100:103], v199 offset:53248
	ds_read_b128 v[216:219], v199 offset:54272
	ds_read_b128 v[220:223], v199 offset:55296
	ds_read_b128 v[224:227], v199 offset:56320
	global_load_lds_dwordx4 v[104:105], off
	s_add_i32 m0, s50, 0x2000
	s_add_u32 s48, s48, 0x80080
	v_lshl_add_u64 v[104:105], v[234:235], 0, s[22:23]
	s_addc_u32 s49, s49, 0
	s_add_i32 s50, s76, s56
	global_load_lds_dwordx4 v[104:105], off
	v_lshl_add_u64 v[104:105], s[48:49], 0, v[182:183]
	s_mov_b32 m0, s50
	s_nop 0
	global_load_lds_dwordx4 v[104:105], off
	v_lshl_add_u64 v[104:105], s[48:49], 0, v[186:187]
	s_add_i32 m0, s50, 0x2000
	s_nop 0
	global_load_lds_dwordx4 v[104:105], off
	v_lshl_add_u64 v[104:105], v[236:237], 0, s[22:23]
	s_mov_b32 m0, s63
	s_nop 0
	global_load_lds_dwordx4 v[104:105], off
	v_lshl_add_u64 v[104:105], v[238:239], 0, s[22:23]
	s_mov_b32 m0, s64
	s_nop 0
	global_load_lds_dwordx4 v[104:105], off
	s_waitcnt vmcnt(8)
	s_waitcnt lgkmcnt(0)
	s_barrier
	s_setprio 1
	s_waitcnt lgkmcnt(0)
	v_mfma_f32_16x16x32_bf16 v[104:107], v[52:55], v[72:75], v[108:111]
	v_mfma_f32_16x16x32_bf16 v[76:79], v[60:63], v[72:75], v[76:79]
	v_mfma_f32_16x16x32_bf16 v[68:71], v[52:55], v[92:95], v[68:71]
	v_mfma_f32_16x16x32_bf16 v[36:39], v[60:63], v[92:95], v[36:39]
	v_mfma_f32_16x16x32_bf16 v[28:31], v[52:55], v[100:103], v[28:31]
	v_mfma_f32_16x16x32_bf16 v[20:23], v[60:63], v[100:103], v[20:23]
	v_mfma_f32_16x16x32_bf16 v[12:15], v[52:55], v[220:223], v[12:15]
	v_mfma_f32_16x16x32_bf16 v[8:11], v[60:63], v[220:223], v[8:11]
	v_mfma_f32_16x16x32_bf16 v[108:111], v[56:59], v[88:91], v[104:107]
	v_mfma_f32_16x16x32_bf16 v[76:79], v[64:67], v[88:91], v[76:79]
	v_mfma_f32_16x16x32_bf16 v[68:71], v[56:59], v[96:99], v[68:71]
	v_mfma_f32_16x16x32_bf16 v[36:39], v[64:67], v[96:99], v[36:39]
	v_mfma_f32_16x16x32_bf16 v[28:31], v[56:59], v[216:219], v[28:31]
	v_mfma_f32_16x16x32_bf16 v[20:23], v[64:67], v[216:219], v[20:23]
	v_mfma_f32_16x16x32_bf16 v[12:15], v[56:59], v[224:227], v[12:15]
	v_mfma_f32_16x16x32_bf16 v[8:11], v[64:67], v[224:227], v[8:11]
	s_setprio 0
	s_setprio 1
	v_mfma_f32_16x16x32_bf16 v[44:47], v[80:83], v[72:75], v[44:47]
	v_mfma_f32_16x16x32_bf16 v[104:107], v[84:87], v[88:91], v[44:47]
	v_mfma_f32_16x16x32_bf16 v[44:47], v[176:179], v[72:75], v[48:51]
	v_mfma_f32_16x16x32_bf16 v[40:43], v[80:83], v[92:95], v[40:43]
	v_mfma_f32_16x16x32_bf16 v[32:35], v[176:179], v[92:95], v[32:35]
	v_mfma_f32_16x16x32_bf16 v[24:27], v[80:83], v[100:103], v[24:27]
	v_mfma_f32_16x16x32_bf16 v[16:19], v[176:179], v[100:103], v[16:19]
	v_mfma_f32_16x16x32_bf16 v[4:7], v[80:83], v[220:223], v[4:7]
	v_mfma_f32_16x16x32_bf16 v[0:3], v[176:179], v[220:223], v[0:3]
	v_mfma_f32_16x16x32_bf16 v[72:75], v[212:215], v[88:91], v[44:47]
	v_mfma_f32_16x16x32_bf16 v[40:43], v[84:87], v[96:99], v[40:43]
	v_mfma_f32_16x16x32_bf16 v[32:35], v[212:215], v[96:99], v[32:35]
	v_mfma_f32_16x16x32_bf16 v[24:27], v[84:87], v[216:219], v[24:27]
	v_mfma_f32_16x16x32_bf16 v[16:19], v[212:215], v[216:219], v[16:19]
	v_mfma_f32_16x16x32_bf16 v[4:7], v[84:87], v[224:227], v[4:7]
	v_mfma_f32_16x16x32_bf16 v[0:3], v[212:215], v[224:227], v[0:3]
	s_setprio 0
	s_add_i32 s74, s74, 2
	s_add_u32 s46, s46, 0x100
	s_addc_u32 s47, s47, 0
	s_add_u32 s72, s72, 0x100
	s_addc_u32 s73, s73, 0
	s_cmp_gt_u32 s74, 29
	s_barrier
	s_cbranch_scc0 .LBB0_479
	s_and_b64 vcc, exec, s[24:25]
	s_cbranch_vccz .LBB0_482
	s_barrier

; #define PG8_STAGE(bufoff, gbase, voff) do { _Pragma("unroll") for (int _i = 0; _i < 2; ++_i) \
;         __builtin_amdgcn_global_load_lds((const unsigned*)((const char*)(gbase) + (voff)[_i]), (PG8_LAS unsigned*)(lds + (bufoff) + ldsw + _i * 8192), 16, 0, 0); } while (0)
; #define PG8_LDA(dst, b, h) do { _Pragma("unroll") for (int m = 0; m < 4; ++m) _Pragma("unroll") for (int k = 0; k < 2; ++k) dst[m][k] = *(const PG8_LAS bf16x8*)(lds + PG8_SA(b, h) + aoff + m * 2048 + k * 1024); } while (0)
; #define PG8_LDB(dst, b, h) do { _Pragma("unroll") for (int n = 0; n < 2; ++n) _Pragma("unroll") for (int k = 0; k < 2; ++k) dst[n][k] = *(const PG8_LAS bf16x8*)(lds + PG8_SB(b, h) + boff + n * 2048 + k * 1024); } while (0)
; #define PG8_MMA(ai, bj, At, Bt) do { __builtin_amdgcn_s_setprio(1); _Pragma("unroll") for (int m = 0; m < 4; ++m) _Pragma("unroll") for (int n = 0; n < 2; ++n) _Pragma("unroll") for (int k = 0; k < 2; ++k) \
;         acc[ai][bj][m][n] = __builtin_amdgcn_mfma_f32_16x16x32_bf16(Bt[n][k], At[m][k], acc[ai][bj][m][n], 0, 0, 0); __builtin_amdgcn_s_setprio(0); } while (0)
; #define PG8_WAIT_V(n) asm volatile("s_waitcnt vmcnt(" #n ")" ::: "memory")
; #define PG8_WAIT_L(n) asm volatile("s_waitcnt lgkmcnt(" #n ")" ::: "memory")
; #define PG8_BAR __builtin_amdgcn_s_barrier()
; template <class Epi, class Sched, bool ALIGN_EPI = false, bool SP2 = false>
; __device__ __forceinline__ void gemm_phase(PG8_LAS unsigned char* lds, const Gemm g, const Sched& S, const Epi& E, const int wave_in) {
;     ...
;         for (int t = 0; t < nt; t += 2) {
;             const bool last = (t == nt - 2);
;             const char* a1 = cA + (size_t)(t + 1) * kstep;
;             const char* a2 = last ? nA : cA + (size_t)(t + 2) * kstep; const char* b2 = last ? nB : cB + (size_t)(t + 2) * kstep;
;             const char* a3 = a2 + kstep; const char* b3 = b2 + kstep;
;             if (last && has_next) S.a_ready(nxt);
;             if constexpr (SP2) {
;             PG8_LDB(B0, 0, 0); PG8_LDB(B1, 0, 1); PG8_SCHED; PG8_LDA(At, 0, 0); PG8_STAGE(PG8_SA(1, 1), a1 + hstepA, voffA);
;             PG8_WAIT_V(8); PG8_WAIT_L(0); PG8_BAR; PG8_MMA(0, 0, At, B0); PG8_MMA(0, 1, At, B1); PG8_BAR; PG8_SCHED;
;             PG8_LDA(At, 0, 1); PG8_STAGE(PG8_SB(0, 0), b2, voffB); PG8_STAGE(PG8_SB(0, 1), b2 + hstepB, voffB); PG8_STAGE(PG8_SA(0, 0), a2, voffA);
.LBB0_1513:
	ds_read_b128 v[144:147], v151
	ds_read_b128 v[154:157], v151 offset:1024
	ds_read_b128 v[158:161], v151 offset:2048
	ds_read_b128 v[162:165], v151 offset:3072
	ds_read_b128 v[166:169], v152
	ds_read_b128 v[170:173], v152 offset:1024
	ds_read_b128 v[174:177], v152 offset:2048
	ds_read_b128 v[178:181], v152 offset:3072
	s_add_u32 s22, s20, 0xfff80080
	s_addc_u32 s23, s21, -1
	s_cmp_eq_u32 s50, 28
	s_cselect_b32 s25, s13, s23
	s_cselect_b32 s24, s46, s22
	s_cselect_b32 s23, s11, s49
	s_cselect_b32 s22, s47, s48
	v_lshl_add_u64 v[214:215], s[20:21], 0, v[136:137]
	s_add_i32 m0, s19, 0xc000
	ds_read_b128 v[182:185], v153
	ds_read_b128 v[186:189], v153 offset:1024
	ds_read_b128 v[190:193], v153 offset:2048
	ds_read_b128 v[194:197], v153 offset:3072
	ds_read_b128 v[198:201], v153 offset:4096
	ds_read_b128 v[202:205], v153 offset:5120
	ds_read_b128 v[206:209], v153 offset:6144
	ds_read_b128 v[210:213], v153 offset:7168
	global_load_lds_dwordx4 v[214:215], off
	v_lshl_add_u64 v[214:215], s[20:21], 0, v[138:139]
	s_add_i32 m0, s19, 0xe000
	s_nop 0
	global_load_lds_dwordx4 v[214:215], off
	s_waitcnt vmcnt(8)
	s_waitcnt lgkmcnt(0)
	s_barrier
	s_setprio 1
	s_waitcnt lgkmcnt(0)
	v_mfma_f32_16x16x32_bf16 v[124:127], v[144:147], v[182:185], v[124:127]
	v_mfma_f32_16x16x32_bf16 v[120:123], v[158:161], v[182:185], v[120:123]
	v_mfma_f32_16x16x32_bf16 v[116:119], v[144:147], v[190:193], v[116:119]
	v_mfma_f32_16x16x32_bf16 v[108:111], v[158:161], v[190:193], v[108:111]
	v_mfma_f32_16x16x32_bf16 v[100:103], v[144:147], v[198:201], v[100:103]
	v_mfma_f32_16x16x32_bf16 v[92:95], v[158:161], v[198:201], v[92:95]
	v_mfma_f32_16x16x32_bf16 v[84:87], v[144:147], v[206:209], v[84:87]
	v_mfma_f32_16x16x32_bf16 v[76:79], v[158:161], v[206:209], v[76:79]
	v_mfma_f32_16x16x32_bf16 v[124:127], v[154:157], v[186:189], v[124:127]
	v_mfma_f32_16x16x32_bf16 v[120:123], v[162:165], v[186:189], v[120:123]
	v_mfma_f32_16x16x32_bf16 v[116:119], v[154:157], v[194:197], v[116:119]
	v_mfma_f32_16x16x32_bf16 v[108:111], v[162:165], v[194:197], v[108:111]
	v_mfma_f32_16x16x32_bf16 v[100:103], v[154:157], v[202:205], v[100:103]
	v_mfma_f32_16x16x32_bf16 v[92:95], v[162:165], v[202:205], v[92:95]
	v_mfma_f32_16x16x32_bf16 v[84:87], v[154:157], v[210:213], v[84:87]
	v_mfma_f32_16x16x32_bf16 v[76:79], v[162:165], v[210:213], v[76:79]
	s_setprio 0
	s_setprio 1
	v_mfma_f32_16x16x32_bf16 v[112:115], v[166:169], v[182:185], v[112:115]
	v_mfma_f32_16x16x32_bf16 v[104:107], v[174:177], v[182:185], v[104:107]
	v_mfma_f32_16x16x32_bf16 v[96:99], v[166:169], v[190:193], v[96:99]
	v_mfma_f32_16x16x32_bf16 v[88:91], v[174:177], v[190:193], v[88:91]
	v_mfma_f32_16x16x32_bf16 v[80:83], v[166:169], v[198:201], v[80:83]
	v_mfma_f32_16x16x32_bf16 v[72:75], v[174:177], v[198:201], v[72:75]
	v_mfma_f32_16x16x32_bf16 v[68:71], v[166:169], v[206:209], v[68:71]
	v_mfma_f32_16x16x32_bf16 v[64:67], v[174:177], v[206:209], v[64:67]
	v_mfma_f32_16x16x32_bf16 v[112:115], v[170:173], v[186:189], v[112:115]
	v_mfma_f32_16x16x32_bf16 v[104:107], v[178:181], v[186:189], v[104:107]
	v_mfma_f32_16x16x32_bf16 v[96:99], v[170:173], v[194:197], v[96:99]
	v_mfma_f32_16x16x32_bf16 v[88:91], v[178:181], v[194:197], v[88:91]
	v_mfma_f32_16x16x32_bf16 v[80:83], v[170:173], v[202:205], v[80:83]
	v_mfma_f32_16x16x32_bf16 v[72:75], v[178:181], v[202:205], v[72:75]
	v_mfma_f32_16x16x32_bf16 v[68:71], v[170:173], v[210:213], v[68:71]
	v_mfma_f32_16x16x32_bf16 v[64:67], v[178:181], v[210:213], v[64:67]
	s_setprio 0
	s_barrier
	s_add_i32 s51, s42, s30
	v_lshl_add_u64 v[214:215], s[22:23], 0, v[132:133]
	s_mov_b32 m0, s51
	ds_read_b128 v[182:185], v153 offset:16384
	ds_read_b128 v[186:189], v153 offset:17408
	ds_read_b128 v[190:193], v153 offset:18432
	ds_read_b128 v[194:197], v153 offset:19456
	ds_read_b128 v[198:201], v153 offset:20480
	ds_read_b128 v[202:205], v153 offset:21504
	ds_read_b128 v[206:209], v153 offset:22528
	ds_read_b128 v[210:213], v153 offset:23552
	global_load_lds_dwordx4 v[214:215], off
	s_add_i32 m0, s51, 0x2000
	s_add_u32 s52, s22, 0x80000
	v_lshl_add_u64 v[216:217], s[22:23], 0, v[128:129]
	s_addc_u32 s53, s23, 0
	s_add_i32 s51, s43, s30
	global_load_lds_dwordx4 v[216:217], off
	v_lshl_add_u64 v[218:219], s[52:53], 0, v[132:133]
	s_mov_b32 m0, s51
	v_lshl_add_u64 v[220:221], s[24:25], 0, v[130:131]
	global_load_lds_dwordx4 v[218:219], off
	v_lshl_add_u64 v[218:219], s[52:53], 0, v[128:129]
	s_add_i32 m0, s51, 0x2000
	s_nop 0
	global_load_lds_dwordx4 v[218:219], off
	v_lshl_add_u64 v[218:219], s[24:25], 0, v[134:135]
	s_mov_b32 m0, s19
	s_nop 0
	global_load_lds_dwordx4 v[218:219], off
	s_mov_b32 m0, s35
	s_nop 0
	global_load_lds_dwordx4 v[220:221], off
	s_waitcnt vmcnt(8)
	s_waitcnt lgkmcnt(0)
	s_barrier
; #define PG8_STAGE(bufoff, gbase, voff) do { _Pragma("unroll") for (int _i = 0; _i < 2; ++_i) \
;         __builtin_amdgcn_global_load_lds((const unsigned*)((const char*)(gbase) + (voff)[_i]), (PG8_LAS unsigned*)(lds + (bufoff) + ldsw + _i * 8192), 16, 0, 0); } while (0)
; #define PG8_LDA(dst, b, h) do { _Pragma("unroll") for (int m = 0; m < 4; ++m) _Pragma("unroll") for (int k = 0; k < 2; ++k) dst[m][k] = *(const PG8_LAS bf16x8*)(lds + PG8_SA(b, h) + aoff + m * 2048 + k * 1024); } while (0)
; #define PG8_LDB(dst, b, h) do { _Pragma("unroll") for (int n = 0; n < 2; ++n) _Pragma("unroll") for (int k = 0; k < 2; ++k) dst[n][k] = *(const PG8_LAS bf16x8*)(lds + PG8_SB(b, h) + boff + n * 2048 + k * 1024); } while (0)
; #define PG8_MMA(ai, bj, At, Bt) do { __builtin_amdgcn_s_setprio(1); _Pragma("unroll") for (int m = 0; m < 4; ++m) _Pragma("unroll") for (int n = 0; n < 2; ++n) _Pragma("unroll") for (int k = 0; k < 2; ++k) \
;         acc[ai][bj][m][n] = __builtin_amdgcn_mfma_f32_16x16x32_bf16(Bt[n][k], At[m][k], acc[ai][bj][m][n], 0, 0, 0); __builtin_amdgcn_s_setprio(0); } while (0)
; #define PG8_WAIT_V(n) asm volatile("s_waitcnt vmcnt(" #n ")" ::: "memory")
; #define PG8_WAIT_L(n) asm volatile("s_waitcnt lgkmcnt(" #n ")" ::: "memory")
; #define PG8_BAR __builtin_amdgcn_s_barrier()
; #define PG8_SCHED __builtin_amdgcn_sched_barrier(0)
; template <class Epi, class Sched, bool ALIGN_EPI = false, bool SP2 = false>
; __device__ __forceinline__ void gemm_phase(PG8_LAS unsigned char* lds, const Gemm g, const Sched& S, const Epi& E, const int wave_in) {
;     ...
;             PG8_WAIT_V(8); PG8_WAIT_L(0); PG8_BAR; PG8_MMA(1, 0, At, B0); PG8_MMA(1, 1, At, B1); PG8_BAR; PG8_SCHED;
;             PG8_LDB(B0, 1, 0); PG8_LDB(B1, 1, 1); PG8_SCHED; PG8_LDA(At, 1, 0); PG8_STAGE(PG8_SA(0, 1), a2 + hstepA, voffA);
;             PG8_WAIT_V(8); PG8_WAIT_L(0); PG8_BAR; PG8_MMA(0, 0, At, B0); PG8_MMA(0, 1, At, B1); PG8_BAR; PG8_SCHED;
	s_setprio 1
	s_waitcnt lgkmcnt(0)
	v_mfma_f32_16x16x32_bf16 v[60:63], v[144:147], v[182:185], v[60:63]
	v_mfma_f32_16x16x32_bf16 v[56:59], v[158:161], v[182:185], v[56:59]
	v_mfma_f32_16x16x32_bf16 v[52:55], v[144:147], v[190:193], v[52:55]
	v_mfma_f32_16x16x32_bf16 v[44:47], v[158:161], v[190:193], v[44:47]
	v_mfma_f32_16x16x32_bf16 v[36:39], v[144:147], v[198:201], v[36:39]
	v_mfma_f32_16x16x32_bf16 v[28:31], v[158:161], v[198:201], v[28:31]
	v_mfma_f32_16x16x32_bf16 v[20:23], v[144:147], v[206:209], v[20:23]
	v_mfma_f32_16x16x32_bf16 v[12:15], v[158:161], v[206:209], v[12:15]
	v_mfma_f32_16x16x32_bf16 v[60:63], v[154:157], v[186:189], v[60:63]
	v_mfma_f32_16x16x32_bf16 v[56:59], v[162:165], v[186:189], v[56:59]
	v_mfma_f32_16x16x32_bf16 v[52:55], v[154:157], v[194:197], v[52:55]
	v_mfma_f32_16x16x32_bf16 v[44:47], v[162:165], v[194:197], v[44:47]
	v_mfma_f32_16x16x32_bf16 v[36:39], v[154:157], v[202:205], v[36:39]
	v_mfma_f32_16x16x32_bf16 v[28:31], v[162:165], v[202:205], v[28:31]
	v_mfma_f32_16x16x32_bf16 v[20:23], v[154:157], v[210:213], v[20:23]
	v_mfma_f32_16x16x32_bf16 v[12:15], v[162:165], v[210:213], v[12:15]
	s_setprio 0
	s_setprio 1
	v_mfma_f32_16x16x32_bf16 v[48:51], v[166:169], v[182:185], v[48:51]
	v_mfma_f32_16x16x32_bf16 v[40:43], v[174:177], v[182:185], v[40:43]
	v_mfma_f32_16x16x32_bf16 v[32:35], v[166:169], v[190:193], v[32:35]
	v_mfma_f32_16x16x32_bf16 v[24:27], v[174:177], v[190:193], v[24:27]
	v_mfma_f32_16x16x32_bf16 v[16:19], v[166:169], v[198:201], v[16:19]
	v_mfma_f32_16x16x32_bf16 v[8:11], v[174:177], v[198:201], v[8:11]
	v_mfma_f32_16x16x32_bf16 v[4:7], v[166:169], v[206:209], v[4:7]
	v_mfma_f32_16x16x32_bf16 v[0:3], v[174:177], v[206:209], v[0:3]
	v_mfma_f32_16x16x32_bf16 v[48:51], v[170:173], v[186:189], v[48:51]
	v_mfma_f32_16x16x32_bf16 v[40:43], v[178:181], v[186:189], v[40:43]
	v_mfma_f32_16x16x32_bf16 v[32:35], v[170:173], v[194:197], v[32:35]
	v_mfma_f32_16x16x32_bf16 v[24:27], v[178:181], v[194:197], v[24:27]
	v_mfma_f32_16x16x32_bf16 v[16:19], v[170:173], v[202:205], v[16:19]
	v_mfma_f32_16x16x32_bf16 v[8:11], v[178:181], v[202:205], v[8:11]
	v_mfma_f32_16x16x32_bf16 v[4:7], v[170:173], v[210:213], v[4:7]
	v_mfma_f32_16x16x32_bf16 v[0:3], v[178:181], v[210:213], v[0:3]
	s_setprio 0
	s_barrier
	s_add_i32 s51, 0, 0x18000
	s_add_i32 s52, 0, 0x1c000
	v_add_u32_e32 v162, s51, v149
	v_add_u32_e32 v178, s52, v149
	ds_read_b128 v[144:147], v162
	ds_read_b128 v[154:157], v162 offset:1024
	ds_read_b128 v[158:161], v162 offset:2048
	ds_read_b128 v[162:165], v162 offset:3072
	ds_read_b128 v[166:169], v178
	ds_read_b128 v[170:173], v178 offset:1024
	ds_read_b128 v[174:177], v178 offset:2048
	ds_read_b128 v[178:181], v178 offset:3072
	s_add_u32 s24, s24, 0x80000
	s_addc_u32 s25, s25, 0
	s_mov_b32 m0, s36
	v_lshl_add_u64 v[222:223], s[24:25], 0, v[134:135]
	ds_read_b128 v[182:185], v153 offset:32768
	ds_read_b128 v[186:189], v153 offset:33792
	ds_read_b128 v[190:193], v153 offset:34816
	ds_read_b128 v[194:197], v153 offset:35840
	ds_read_b128 v[198:201], v153 offset:36864
	ds_read_b128 v[202:205], v153 offset:37888
	ds_read_b128 v[206:209], v153 offset:38912
	ds_read_b128 v[210:213], v153 offset:39936
	global_load_lds_dwordx4 v[222:223], off
	v_lshl_add_u64 v[222:223], s[24:25], 0, v[130:131]
	s_mov_b32 m0, s37
	s_nop 0
	global_load_lds_dwordx4 v[222:223], off
	s_waitcnt vmcnt(8)
	s_waitcnt lgkmcnt(0)
	s_barrier
	s_setprio 1
	s_waitcnt lgkmcnt(0)
	v_mfma_f32_16x16x32_bf16 v[124:127], v[144:147], v[182:185], v[124:127]
	v_mfma_f32_16x16x32_bf16 v[120:123], v[158:161], v[182:185], v[120:123]
	v_mfma_f32_16x16x32_bf16 v[116:119], v[144:147], v[190:193], v[116:119]
	v_mfma_f32_16x16x32_bf16 v[108:111], v[158:161], v[190:193], v[108:111]
	v_mfma_f32_16x16x32_bf16 v[100:103], v[144:147], v[198:201], v[100:103]
	v_mfma_f32_16x16x32_bf16 v[92:95], v[158:161], v[198:201], v[92:95]
	v_mfma_f32_16x16x32_bf16 v[84:87], v[144:147], v[206:209], v[84:87]
	v_mfma_f32_16x16x32_bf16 v[76:79], v[158:161], v[206:209], v[76:79]
	v_mfma_f32_16x16x32_bf16 v[124:127], v[154:157], v[186:189], v[124:127]
	v_mfma_f32_16x16x32_bf16 v[120:123], v[162:165], v[186:189], v[120:123]
	v_mfma_f32_16x16x32_bf16 v[116:119], v[154:157], v[194:197], v[116:119]
	v_mfma_f32_16x16x32_bf16 v[108:111], v[162:165], v[194:197], v[108:111]
	v_mfma_f32_16x16x32_bf16 v[100:103], v[154:157], v[202:205], v[100:103]
	v_mfma_f32_16x16x32_bf16 v[92:95], v[162:165], v[202:205], v[92:95]
	v_mfma_f32_16x16x32_bf16 v[84:87], v[154:157], v[210:213], v[84:87]
	v_mfma_f32_16x16x32_bf16 v[76:79], v[162:165], v[210:213], v[76:79]
	s_setprio 0
	s_setprio 1
	v_mfma_f32_16x16x32_bf16 v[112:115], v[166:169], v[182:185], v[112:115]
	v_mfma_f32_16x16x32_bf16 v[104:107], v[174:177], v[182:185], v[104:107]
	v_mfma_f32_16x16x32_bf16 v[96:99], v[166:169], v[190:193], v[96:99]
	v_mfma_f32_16x16x32_bf16 v[88:91], v[174:177], v[190:193], v[88:91]
	v_mfma_f32_16x16x32_bf16 v[80:83], v[166:169], v[198:201], v[80:83]
	v_mfma_f32_16x16x32_bf16 v[72:75], v[174:177], v[198:201], v[72:75]
	v_mfma_f32_16x16x32_bf16 v[68:71], v[166:169], v[206:209], v[68:71]
	v_mfma_f32_16x16x32_bf16 v[64:67], v[174:177], v[206:209], v[64:67]
	v_mfma_f32_16x16x32_bf16 v[112:115], v[170:173], v[186:189], v[112:115]
	v_mfma_f32_16x16x32_bf16 v[104:107], v[178:181], v[186:189], v[104:107]
	v_mfma_f32_16x16x32_bf16 v[96:99], v[170:173], v[194:197], v[96:99]
	v_mfma_f32_16x16x32_bf16 v[88:91], v[178:181], v[194:197], v[88:91]
	v_mfma_f32_16x16x32_bf16 v[80:83], v[170:173], v[202:205], v[80:83]
	v_mfma_f32_16x16x32_bf16 v[72:75], v[178:181], v[202:205], v[72:75]
	v_mfma_f32_16x16x32_bf16 v[68:71], v[170:173], v[210:213], v[68:71]
	v_mfma_f32_16x16x32_bf16 v[64:67], v[178:181], v[210:213], v[64:67]
	s_setprio 0
	s_barrier
; #define PG8_STAGE(bufoff, gbase, voff) do { _Pragma("unroll") for (int _i = 0; _i < 2; ++_i) \
;         __builtin_amdgcn_global_load_lds((const unsigned*)((const char*)(gbase) + (voff)[_i]), (PG8_LAS unsigned*)(lds + (bufoff) + ldsw + _i * 8192), 16, 0, 0); } while (0)
; #define PG8_LDA(dst, b, h) do { _Pragma("unroll") for (int m = 0; m < 4; ++m) _Pragma("unroll") for (int k = 0; k < 2; ++k) dst[m][k] = *(const PG8_LAS bf16x8*)(lds + PG8_SA(b, h) + aoff + m * 2048 + k * 1024); } while (0)
; #define PG8_MMA(ai, bj, At, Bt) do { __builtin_amdgcn_s_setprio(1); _Pragma("unroll") for (int m = 0; m < 4; ++m) _Pragma("unroll") for (int n = 0; n < 2; ++n) _Pragma("unroll") for (int k = 0; k < 2; ++k) \
;         acc[ai][bj][m][n] = __builtin_amdgcn_mfma_f32_16x16x32_bf16(Bt[n][k], At[m][k], acc[ai][bj][m][n], 0, 0, 0); __builtin_amdgcn_s_setprio(0); } while (0)
; #define PG8_WAIT_V(n) asm volatile("s_waitcnt vmcnt(" #n ")" ::: "memory")
; #define PG8_WAIT_L(n) asm volatile("s_waitcnt lgkmcnt(" #n ")" ::: "memory")
; #define PG8_BAR __builtin_amdgcn_s_barrier()
; #define PG8_SCHED __builtin_amdgcn_sched_barrier(0)
; template <class Epi, class Sched, bool ALIGN_EPI = false, bool SP2 = false>
; __device__ __forceinline__ void gemm_phase(PG8_LAS unsigned char* lds, const Gemm g, const Sched& S, const Epi& E, const int wave_in) {
;     ...
;         for (int t = 0; t < nt; t += 2) {
;             const bool last = (t == nt - 2);
;     ...
;             PG8_LDA(At, 1, 1); PG8_STAGE(PG8_SB(1, 0), b3, voffB); PG8_STAGE(PG8_SB(1, 1), b3 + hstepB, voffB); PG8_STAGE(PG8_SA(1, 0), a3, voffA);
;             PG8_WAIT_V(8); PG8_WAIT_L(0); PG8_BAR; PG8_MMA(1, 0, At, B0); PG8_MMA(1, 1, At, B1); PG8_BAR; PG8_SCHED;
	s_add_i32 s24, s51, s30
	v_lshl_add_u64 v[214:215], v[214:215], 0, s[6:7]
	s_mov_b32 m0, s24
	ds_read_b128 v[182:185], v153 offset:49152
	ds_read_b128 v[186:189], v153 offset:50176
	ds_read_b128 v[190:193], v153 offset:51200
	ds_read_b128 v[194:197], v153 offset:52224
	ds_read_b128 v[198:201], v153 offset:53248
	ds_read_b128 v[202:205], v153 offset:54272
	ds_read_b128 v[206:209], v153 offset:55296
	ds_read_b128 v[210:213], v153 offset:56320
	global_load_lds_dwordx4 v[214:215], off
	s_add_i32 m0, s24, 0x2000
	s_add_u32 s22, s22, 0x80080
	v_lshl_add_u64 v[214:215], v[216:217], 0, s[6:7]
	s_addc_u32 s23, s23, 0
	s_add_i32 s24, s52, s30
	global_load_lds_dwordx4 v[214:215], off
	v_lshl_add_u64 v[214:215], s[22:23], 0, v[132:133]
	s_mov_b32 m0, s24
	s_nop 0
	global_load_lds_dwordx4 v[214:215], off
	v_lshl_add_u64 v[214:215], s[22:23], 0, v[128:129]
	s_add_i32 m0, s24, 0x2000
	s_nop 0
	global_load_lds_dwordx4 v[214:215], off
	v_lshl_add_u64 v[214:215], v[218:219], 0, s[6:7]
	s_mov_b32 m0, s39
	s_nop 0
	global_load_lds_dwordx4 v[214:215], off
	v_lshl_add_u64 v[214:215], v[220:221], 0, s[6:7]
	s_mov_b32 m0, s40
	s_nop 0
	global_load_lds_dwordx4 v[214:215], off
	s_waitcnt vmcnt(8)
	s_waitcnt lgkmcnt(0)
	s_barrier
	s_setprio 1
	s_waitcnt lgkmcnt(0)
	v_mfma_f32_16x16x32_bf16 v[60:63], v[144:147], v[182:185], v[60:63]
	v_mfma_f32_16x16x32_bf16 v[56:59], v[158:161], v[182:185], v[56:59]
	v_mfma_f32_16x16x32_bf16 v[52:55], v[144:147], v[190:193], v[52:55]
	v_mfma_f32_16x16x32_bf16 v[44:47], v[158:161], v[190:193], v[44:47]
	v_mfma_f32_16x16x32_bf16 v[36:39], v[144:147], v[198:201], v[36:39]
	v_mfma_f32_16x16x32_bf16 v[28:31], v[158:161], v[198:201], v[28:31]
	v_mfma_f32_16x16x32_bf16 v[20:23], v[144:147], v[206:209], v[20:23]
	v_mfma_f32_16x16x32_bf16 v[12:15], v[158:161], v[206:209], v[12:15]
	v_mfma_f32_16x16x32_bf16 v[60:63], v[154:157], v[186:189], v[60:63]
	v_mfma_f32_16x16x32_bf16 v[56:59], v[162:165], v[186:189], v[56:59]
	v_mfma_f32_16x16x32_bf16 v[52:55], v[154:157], v[194:197], v[52:55]
	v_mfma_f32_16x16x32_bf16 v[44:47], v[162:165], v[194:197], v[44:47]
	v_mfma_f32_16x16x32_bf16 v[36:39], v[154:157], v[202:205], v[36:39]
	v_mfma_f32_16x16x32_bf16 v[28:31], v[162:165], v[202:205], v[28:31]
	v_mfma_f32_16x16x32_bf16 v[20:23], v[154:157], v[210:213], v[20:23]
	v_mfma_f32_16x16x32_bf16 v[12:15], v[162:165], v[210:213], v[12:15]
	s_setprio 0
	s_setprio 1
	v_mfma_f32_16x16x32_bf16 v[48:51], v[166:169], v[182:185], v[48:51]
	v_mfma_f32_16x16x32_bf16 v[40:43], v[174:177], v[182:185], v[40:43]
	v_mfma_f32_16x16x32_bf16 v[32:35], v[166:169], v[190:193], v[32:35]
	v_mfma_f32_16x16x32_bf16 v[24:27], v[174:177], v[190:193], v[24:27]
	v_mfma_f32_16x16x32_bf16 v[16:19], v[166:169], v[198:201], v[16:19]
	v_mfma_f32_16x16x32_bf16 v[8:11], v[174:177], v[198:201], v[8:11]
	v_mfma_f32_16x16x32_bf16 v[4:7], v[166:169], v[206:209], v[4:7]
	v_mfma_f32_16x16x32_bf16 v[0:3], v[174:177], v[206:209], v[0:3]
	v_mfma_f32_16x16x32_bf16 v[48:51], v[170:173], v[186:189], v[48:51]
	v_mfma_f32_16x16x32_bf16 v[40:43], v[178:181], v[186:189], v[40:43]
	v_mfma_f32_16x16x32_bf16 v[32:35], v[170:173], v[194:197], v[32:35]
	v_mfma_f32_16x16x32_bf16 v[24:27], v[178:181], v[194:197], v[24:27]
	v_mfma_f32_16x16x32_bf16 v[16:19], v[170:173], v[202:205], v[16:19]
	v_mfma_f32_16x16x32_bf16 v[8:11], v[178:181], v[202:205], v[8:11]
	v_mfma_f32_16x16x32_bf16 v[4:7], v[170:173], v[210:213], v[4:7]
	v_mfma_f32_16x16x32_bf16 v[0:3], v[178:181], v[210:213], v[0:3]
	s_setprio 0
	s_add_i32 s50, s50, 2
	s_add_u32 s20, s20, 0x100
	s_addc_u32 s21, s21, 0
	s_add_u32 s48, s48, 0x100
	s_addc_u32 s49, s49, 0
	s_cmp_gt_u32 s50, 29
	s_barrier
	s_cbranch_scc0 .LBB0_1513
	s_and_b64 vcc, exec, s[8:9]
	s_cbranch_vccz .LBB0_1516
	s_barrier

; #define PG8_STAGE(bufoff, gbase, voff) do { _Pragma("unroll") for (int _i = 0; _i < 2; ++_i) \
;         __builtin_amdgcn_global_load_lds((const unsigned*)((const char*)(gbase) + (voff)[_i]), (PG8_LAS unsigned*)(lds + (bufoff) + ldsw + _i * 8192), 16, 0, 0); } while (0)
; #define PG8_LDA(dst, b, h) do { _Pragma("unroll") for (int m = 0; m < 4; ++m) _Pragma("unroll") for (int k = 0; k < 2; ++k) dst[m][k] = *(const PG8_LAS bf16x8*)(lds + PG8_SA(b, h) + aoff + m * 2048 + k * 1024); } while (0)
; #define PG8_LDB(dst, b, h) do { _Pragma("unroll") for (int n = 0; n < 2; ++n) _Pragma("unroll") for (int k = 0; k < 2; ++k) dst[n][k] = *(const PG8_LAS bf16x8*)(lds + PG8_SB(b, h) + boff + n * 2048 + k * 1024); } while (0)
; #define PG8_MMA(ai, bj, At, Bt) do { __builtin_amdgcn_s_setprio(1); _Pragma("unroll") for (int m = 0; m < 4; ++m) _Pragma("unroll") for (int n = 0; n < 2; ++n) _Pragma("unroll") for (int k = 0; k < 2; ++k) \
;         acc[ai][bj][m][n] = __builtin_amdgcn_mfma_f32_16x16x32_bf16(Bt[n][k], At[m][k], acc[ai][bj][m][n], 0, 0, 0); __builtin_amdgcn_s_setprio(0); } while (0)
; #define PG8_WAIT_V(n) asm volatile("s_waitcnt vmcnt(" #n ")" ::: "memory")
; #define PG8_WAIT_L(n) asm volatile("s_waitcnt lgkmcnt(" #n ")" ::: "memory")
; #define PG8_BAR __builtin_amdgcn_s_barrier()
; template <class Epi, class Sched, bool ALIGN_EPI = false, bool SP2 = false>
; __device__ __forceinline__ void gemm_phase(PG8_LAS unsigned char* lds, const Gemm g, const Sched& S, const Epi& E, const int wave_in) {
;     ...
;         for (int t = 0; t < nt; t += 2) {
;             const bool last = (t == nt - 2);
;             const char* a1 = cA + (size_t)(t + 1) * kstep;
;             const char* a2 = last ? nA : cA + (size_t)(t + 2) * kstep; const char* b2 = last ? nB : cB + (size_t)(t + 2) * kstep;
;             const char* a3 = a2 + kstep; const char* b3 = b2 + kstep;
;             if (last && has_next) S.a_ready(nxt);
;             if constexpr (SP2) {
;             PG8_LDB(B0, 0, 0); PG8_LDB(B1, 0, 1); PG8_SCHED; PG8_LDA(At, 0, 0); PG8_STAGE(PG8_SA(1, 1), a1 + hstepA, voffA);
;             PG8_WAIT_V(8); PG8_WAIT_L(0); PG8_BAR; PG8_MMA(0, 0, At, B0); PG8_MMA(0, 1, At, B1); PG8_BAR; PG8_SCHED;
;             PG8_LDA(At, 0, 1); PG8_STAGE(PG8_SB(0, 0), b2, voffB); PG8_STAGE(PG8_SB(0, 1), b2 + hstepB, voffB); PG8_STAGE(PG8_SA(0, 0), a2, voffA);
.LBB0_1825:
	ds_read_b128 v[128:131], v214
	ds_read_b128 v[132:135], v214 offset:1024
	ds_read_b128 v[136:139], v214 offset:2048
	ds_read_b128 v[140:143], v214 offset:3072
	ds_read_b128 v[162:165], v215
	ds_read_b128 v[166:169], v215 offset:1024
	ds_read_b128 v[170:173], v215 offset:2048
	ds_read_b128 v[174:177], v215 offset:3072
	s_add_u32 s28, s26, 0xfff80080
	s_addc_u32 s29, s27, -1
	s_cmp_eq_u32 s61, 28
	s_cselect_b32 s31, s19, s29
	s_cselect_b32 s30, s25, s28
	s_cselect_b32 s29, s17, s60
	s_cselect_b32 s28, s58, s59
	v_lshl_add_u64 v[210:211], s[26:27], 0, v[154:155]
	s_add_i32 m0, s41, 0xc000
	ds_read_b128 v[178:181], v216
	ds_read_b128 v[182:185], v216 offset:1024
	ds_read_b128 v[186:189], v216 offset:2048
	ds_read_b128 v[190:193], v216 offset:3072
	ds_read_b128 v[194:197], v216 offset:4096
	ds_read_b128 v[198:201], v216 offset:5120
	ds_read_b128 v[202:205], v216 offset:6144
	ds_read_b128 v[206:209], v216 offset:7168
	global_load_lds_dwordx4 v[210:211], off
	v_lshl_add_u64 v[210:211], s[26:27], 0, v[156:157]
	s_add_i32 m0, s41, 0xe000
	s_nop 0
	global_load_lds_dwordx4 v[210:211], off
	s_waitcnt vmcnt(8)
	s_waitcnt lgkmcnt(0)
	s_barrier
	s_setprio 1
	s_waitcnt lgkmcnt(0)
	v_mfma_f32_16x16x32_bf16 v[124:127], v[128:131], v[178:181], v[124:127]
	v_mfma_f32_16x16x32_bf16 v[120:123], v[136:139], v[178:181], v[120:123]
	v_mfma_f32_16x16x32_bf16 v[112:115], v[128:131], v[186:189], v[112:115]
	v_mfma_f32_16x16x32_bf16 v[104:107], v[136:139], v[186:189], v[104:107]
	v_mfma_f32_16x16x32_bf16 v[100:103], v[128:131], v[194:197], v[100:103]
	v_mfma_f32_16x16x32_bf16 v[96:99], v[136:139], v[194:197], v[96:99]
	v_mfma_f32_16x16x32_bf16 v[76:79], v[128:131], v[202:205], v[76:79]
	v_mfma_f32_16x16x32_bf16 v[72:75], v[136:139], v[202:205], v[72:75]
	v_mfma_f32_16x16x32_bf16 v[124:127], v[132:135], v[182:185], v[124:127]
	v_mfma_f32_16x16x32_bf16 v[120:123], v[140:143], v[182:185], v[120:123]
	v_mfma_f32_16x16x32_bf16 v[112:115], v[132:135], v[190:193], v[112:115]
	v_mfma_f32_16x16x32_bf16 v[104:107], v[140:143], v[190:193], v[104:107]
	v_mfma_f32_16x16x32_bf16 v[100:103], v[132:135], v[198:201], v[100:103]
	v_mfma_f32_16x16x32_bf16 v[96:99], v[140:143], v[198:201], v[96:99]
	v_mfma_f32_16x16x32_bf16 v[76:79], v[132:135], v[206:209], v[76:79]
	v_mfma_f32_16x16x32_bf16 v[72:75], v[140:143], v[206:209], v[72:75]
	s_setprio 0
	s_setprio 1
	v_mfma_f32_16x16x32_bf16 v[116:119], v[162:165], v[178:181], v[116:119]
	v_mfma_f32_16x16x32_bf16 v[108:111], v[170:173], v[178:181], v[108:111]
	v_mfma_f32_16x16x32_bf16 v[92:95], v[162:165], v[186:189], v[92:95]
	v_mfma_f32_16x16x32_bf16 v[88:91], v[170:173], v[186:189], v[88:91]
	v_mfma_f32_16x16x32_bf16 v[84:87], v[162:165], v[194:197], v[84:87]
	v_mfma_f32_16x16x32_bf16 v[80:83], v[170:173], v[194:197], v[80:83]
	v_mfma_f32_16x16x32_bf16 v[68:71], v[162:165], v[202:205], v[68:71]
	v_mfma_f32_16x16x32_bf16 v[64:67], v[170:173], v[202:205], v[64:67]
	v_mfma_f32_16x16x32_bf16 v[116:119], v[166:169], v[182:185], v[116:119]
	v_mfma_f32_16x16x32_bf16 v[108:111], v[174:177], v[182:185], v[108:111]
	v_mfma_f32_16x16x32_bf16 v[92:95], v[166:169], v[190:193], v[92:95]
	v_mfma_f32_16x16x32_bf16 v[88:91], v[174:177], v[190:193], v[88:91]
	v_mfma_f32_16x16x32_bf16 v[84:87], v[166:169], v[198:201], v[84:87]
	v_mfma_f32_16x16x32_bf16 v[80:83], v[174:177], v[198:201], v[80:83]
	v_mfma_f32_16x16x32_bf16 v[68:71], v[166:169], v[206:209], v[68:71]
	v_mfma_f32_16x16x32_bf16 v[64:67], v[174:177], v[206:209], v[64:67]
	s_setprio 0
	s_barrier
	s_add_i32 s62, s51, s38
	v_lshl_add_u64 v[210:211], s[28:29], 0, v[148:149]
	s_mov_b32 m0, s62
	ds_read_b128 v[178:181], v216 offset:16384
	ds_read_b128 v[182:185], v216 offset:17408
	ds_read_b128 v[186:189], v216 offset:18432
	ds_read_b128 v[190:193], v216 offset:19456
	ds_read_b128 v[194:197], v216 offset:20480
	ds_read_b128 v[198:201], v216 offset:21504
	ds_read_b128 v[202:205], v216 offset:22528
	ds_read_b128 v[206:209], v216 offset:23552
	global_load_lds_dwordx4 v[210:211], off
	s_add_i32 m0, s62, 0x2000
	s_add_u32 s62, s28, 0x80000
	v_lshl_add_u64 v[218:219], s[28:29], 0, v[144:145]
	s_addc_u32 s63, s29, 0
	s_add_i32 s64, s52, s38
	global_load_lds_dwordx4 v[218:219], off
	v_lshl_add_u64 v[220:221], s[62:63], 0, v[148:149]
	s_mov_b32 m0, s64
	v_lshl_add_u64 v[222:223], s[30:31], 0, v[146:147]
	global_load_lds_dwordx4 v[220:221], off
	v_lshl_add_u64 v[220:221], s[62:63], 0, v[144:145]
	s_add_i32 m0, s64, 0x2000
	s_nop 0
	global_load_lds_dwordx4 v[220:221], off
	v_lshl_add_u64 v[220:221], s[30:31], 0, v[150:151]
	s_mov_b32 m0, s41
	s_nop 0
	global_load_lds_dwordx4 v[220:221], off
	s_mov_b32 m0, s42
	s_nop 0
	global_load_lds_dwordx4 v[222:223], off
	s_waitcnt vmcnt(8)
	s_waitcnt lgkmcnt(0)
	s_barrier
; #define PG8_STAGE(bufoff, gbase, voff) do { _Pragma("unroll") for (int _i = 0; _i < 2; ++_i) \
;         __builtin_amdgcn_global_load_lds((const unsigned*)((const char*)(gbase) + (voff)[_i]), (PG8_LAS unsigned*)(lds + (bufoff) + ldsw + _i * 8192), 16, 0, 0); } while (0)
; #define PG8_LDA(dst, b, h) do { _Pragma("unroll") for (int m = 0; m < 4; ++m) _Pragma("unroll") for (int k = 0; k < 2; ++k) dst[m][k] = *(const PG8_LAS bf16x8*)(lds + PG8_SA(b, h) + aoff + m * 2048 + k * 1024); } while (0)
; #define PG8_LDB(dst, b, h) do { _Pragma("unroll") for (int n = 0; n < 2; ++n) _Pragma("unroll") for (int k = 0; k < 2; ++k) dst[n][k] = *(const PG8_LAS bf16x8*)(lds + PG8_SB(b, h) + boff + n * 2048 + k * 1024); } while (0)
; #define PG8_MMA(ai, bj, At, Bt) do { __builtin_amdgcn_s_setprio(1); _Pragma("unroll") for (int m = 0; m < 4; ++m) _Pragma("unroll") for (int n = 0; n < 2; ++n) _Pragma("unroll") for (int k = 0; k < 2; ++k) \
;         acc[ai][bj][m][n] = __builtin_amdgcn_mfma_f32_16x16x32_bf16(Bt[n][k], At[m][k], acc[ai][bj][m][n], 0, 0, 0); __builtin_amdgcn_s_setprio(0); } while (0)
; #define PG8_WAIT_V(n) asm volatile("s_waitcnt vmcnt(" #n ")" ::: "memory")
; #define PG8_WAIT_L(n) asm volatile("s_waitcnt lgkmcnt(" #n ")" ::: "memory")
; #define PG8_BAR __builtin_amdgcn_s_barrier()
; #define PG8_SCHED __builtin_amdgcn_sched_barrier(0)
; template <class Epi, class Sched, bool ALIGN_EPI = false, bool SP2 = false>
; __device__ __forceinline__ void gemm_phase(PG8_LAS unsigned char* lds, const Gemm g, const Sched& S, const Epi& E, const int wave_in) {
;     ...
;             PG8_WAIT_V(8); PG8_WAIT_L(0); PG8_BAR; PG8_MMA(1, 0, At, B0); PG8_MMA(1, 1, At, B1); PG8_BAR; PG8_SCHED;
;             PG8_LDB(B0, 1, 0); PG8_LDB(B1, 1, 1); PG8_SCHED; PG8_LDA(At, 1, 0); PG8_STAGE(PG8_SA(0, 1), a2 + hstepA, voffA);
;             PG8_WAIT_V(8); PG8_WAIT_L(0); PG8_BAR; PG8_MMA(0, 0, At, B0); PG8_MMA(0, 1, At, B1); PG8_BAR; PG8_SCHED;
	s_setprio 1
	s_waitcnt lgkmcnt(0)
	v_mfma_f32_16x16x32_bf16 v[60:63], v[128:131], v[178:181], v[60:63]
	v_mfma_f32_16x16x32_bf16 v[56:59], v[136:139], v[178:181], v[56:59]
	v_mfma_f32_16x16x32_bf16 v[48:51], v[128:131], v[186:189], v[48:51]
	v_mfma_f32_16x16x32_bf16 v[40:43], v[136:139], v[186:189], v[40:43]
	v_mfma_f32_16x16x32_bf16 v[32:35], v[128:131], v[194:197], v[32:35]
	v_mfma_f32_16x16x32_bf16 v[24:27], v[136:139], v[194:197], v[24:27]
	v_mfma_f32_16x16x32_bf16 v[16:19], v[128:131], v[202:205], v[16:19]
	v_mfma_f32_16x16x32_bf16 v[8:11], v[136:139], v[202:205], v[8:11]
	v_mfma_f32_16x16x32_bf16 v[60:63], v[132:135], v[182:185], v[60:63]
	v_mfma_f32_16x16x32_bf16 v[56:59], v[140:143], v[182:185], v[56:59]
	v_mfma_f32_16x16x32_bf16 v[48:51], v[132:135], v[190:193], v[48:51]
	v_mfma_f32_16x16x32_bf16 v[40:43], v[140:143], v[190:193], v[40:43]
	v_mfma_f32_16x16x32_bf16 v[32:35], v[132:135], v[198:201], v[32:35]
	v_mfma_f32_16x16x32_bf16 v[24:27], v[140:143], v[198:201], v[24:27]
	v_mfma_f32_16x16x32_bf16 v[16:19], v[132:135], v[206:209], v[16:19]
	v_mfma_f32_16x16x32_bf16 v[8:11], v[140:143], v[206:209], v[8:11]
	s_setprio 0
	s_setprio 1
	v_mfma_f32_16x16x32_bf16 v[52:55], v[162:165], v[178:181], v[52:55]
	v_mfma_f32_16x16x32_bf16 v[44:47], v[170:173], v[178:181], v[44:47]
	v_mfma_f32_16x16x32_bf16 v[36:39], v[162:165], v[186:189], v[36:39]
	v_mfma_f32_16x16x32_bf16 v[28:31], v[170:173], v[186:189], v[28:31]
	v_mfma_f32_16x16x32_bf16 v[20:23], v[162:165], v[194:197], v[20:23]
	v_mfma_f32_16x16x32_bf16 v[12:15], v[170:173], v[194:197], v[12:15]
	v_mfma_f32_16x16x32_bf16 v[4:7], v[162:165], v[202:205], v[4:7]
	v_mfma_f32_16x16x32_bf16 v[0:3], v[170:173], v[202:205], v[0:3]
	v_mfma_f32_16x16x32_bf16 v[52:55], v[166:169], v[182:185], v[52:55]
	v_mfma_f32_16x16x32_bf16 v[44:47], v[174:177], v[182:185], v[44:47]
	v_mfma_f32_16x16x32_bf16 v[36:39], v[166:169], v[190:193], v[36:39]
	v_mfma_f32_16x16x32_bf16 v[28:31], v[174:177], v[190:193], v[28:31]
	v_mfma_f32_16x16x32_bf16 v[20:23], v[166:169], v[198:201], v[20:23]
	v_mfma_f32_16x16x32_bf16 v[12:15], v[174:177], v[198:201], v[12:15]
	v_mfma_f32_16x16x32_bf16 v[4:7], v[166:169], v[206:209], v[4:7]
	v_mfma_f32_16x16x32_bf16 v[0:3], v[174:177], v[206:209], v[0:3]
	s_setprio 0
	s_barrier
	s_add_i32 s62, 0, 0x18000
	s_add_i32 s63, 0, 0x1c000
	v_add_u32_e32 v140, s62, v212
	v_add_u32_e32 v174, s63, v212
	ds_read_b128 v[128:131], v140
	ds_read_b128 v[132:135], v140 offset:1024
	ds_read_b128 v[136:139], v140 offset:2048
	ds_read_b128 v[140:143], v140 offset:3072
	ds_read_b128 v[162:165], v174
	ds_read_b128 v[166:169], v174 offset:1024
	ds_read_b128 v[170:173], v174 offset:2048
	ds_read_b128 v[174:177], v174 offset:3072
	s_add_u32 s30, s30, 0x80000
	s_addc_u32 s31, s31, 0
	s_mov_b32 m0, s43
	v_lshl_add_u64 v[224:225], s[30:31], 0, v[150:151]
	ds_read_b128 v[178:181], v216 offset:32768
	ds_read_b128 v[182:185], v216 offset:33792
	ds_read_b128 v[186:189], v216 offset:34816
	ds_read_b128 v[190:193], v216 offset:35840
	ds_read_b128 v[194:197], v216 offset:36864
	ds_read_b128 v[198:201], v216 offset:37888
	ds_read_b128 v[202:205], v216 offset:38912
	ds_read_b128 v[206:209], v216 offset:39936
	global_load_lds_dwordx4 v[224:225], off
	v_lshl_add_u64 v[224:225], s[30:31], 0, v[146:147]
	s_mov_b32 m0, s44
	s_nop 0
	global_load_lds_dwordx4 v[224:225], off
	s_waitcnt vmcnt(8)
	s_waitcnt lgkmcnt(0)
	s_barrier
	s_setprio 1
	s_waitcnt lgkmcnt(0)
	v_mfma_f32_16x16x32_bf16 v[124:127], v[128:131], v[178:181], v[124:127]
	v_mfma_f32_16x16x32_bf16 v[120:123], v[136:139], v[178:181], v[120:123]
	v_mfma_f32_16x16x32_bf16 v[112:115], v[128:131], v[186:189], v[112:115]
	v_mfma_f32_16x16x32_bf16 v[104:107], v[136:139], v[186:189], v[104:107]
	v_mfma_f32_16x16x32_bf16 v[100:103], v[128:131], v[194:197], v[100:103]
	v_mfma_f32_16x16x32_bf16 v[96:99], v[136:139], v[194:197], v[96:99]
	v_mfma_f32_16x16x32_bf16 v[76:79], v[128:131], v[202:205], v[76:79]
	v_mfma_f32_16x16x32_bf16 v[72:75], v[136:139], v[202:205], v[72:75]
	v_mfma_f32_16x16x32_bf16 v[124:127], v[132:135], v[182:185], v[124:127]
	v_mfma_f32_16x16x32_bf16 v[120:123], v[140:143], v[182:185], v[120:123]
	v_mfma_f32_16x16x32_bf16 v[112:115], v[132:135], v[190:193], v[112:115]
	v_mfma_f32_16x16x32_bf16 v[104:107], v[140:143], v[190:193], v[104:107]
	v_mfma_f32_16x16x32_bf16 v[100:103], v[132:135], v[198:201], v[100:103]
	v_mfma_f32_16x16x32_bf16 v[96:99], v[140:143], v[198:201], v[96:99]
	v_mfma_f32_16x16x32_bf16 v[76:79], v[132:135], v[206:209], v[76:79]
	v_mfma_f32_16x16x32_bf16 v[72:75], v[140:143], v[206:209], v[72:75]
	s_setprio 0
	s_setprio 1
	v_mfma_f32_16x16x32_bf16 v[116:119], v[162:165], v[178:181], v[116:119]
	v_mfma_f32_16x16x32_bf16 v[108:111], v[170:173], v[178:181], v[108:111]
	v_mfma_f32_16x16x32_bf16 v[92:95], v[162:165], v[186:189], v[92:95]
	v_mfma_f32_16x16x32_bf16 v[88:91], v[170:173], v[186:189], v[88:91]
	v_mfma_f32_16x16x32_bf16 v[84:87], v[162:165], v[194:197], v[84:87]
	v_mfma_f32_16x16x32_bf16 v[80:83], v[170:173], v[194:197], v[80:83]
	v_mfma_f32_16x16x32_bf16 v[68:71], v[162:165], v[202:205], v[68:71]
	v_mfma_f32_16x16x32_bf16 v[64:67], v[170:173], v[202:205], v[64:67]
	v_mfma_f32_16x16x32_bf16 v[116:119], v[166:169], v[182:185], v[116:119]
	v_mfma_f32_16x16x32_bf16 v[108:111], v[174:177], v[182:185], v[108:111]
	v_mfma_f32_16x16x32_bf16 v[92:95], v[166:169], v[190:193], v[92:95]
	v_mfma_f32_16x16x32_bf16 v[88:91], v[174:177], v[190:193], v[88:91]
	v_mfma_f32_16x16x32_bf16 v[84:87], v[166:169], v[198:201], v[84:87]
	v_mfma_f32_16x16x32_bf16 v[80:83], v[174:177], v[198:201], v[80:83]
	v_mfma_f32_16x16x32_bf16 v[68:71], v[166:169], v[206:209], v[68:71]
	v_mfma_f32_16x16x32_bf16 v[64:67], v[174:177], v[206:209], v[64:67]
	s_setprio 0
	s_barrier
; #define PG8_STAGE(bufoff, gbase, voff) do { _Pragma("unroll") for (int _i = 0; _i < 2; ++_i) \
;         __builtin_amdgcn_global_load_lds((const unsigned*)((const char*)(gbase) + (voff)[_i]), (PG8_LAS unsigned*)(lds + (bufoff) + ldsw + _i * 8192), 16, 0, 0); } while (0)
; #define PG8_LDA(dst, b, h) do { _Pragma("unroll") for (int m = 0; m < 4; ++m) _Pragma("unroll") for (int k = 0; k < 2; ++k) dst[m][k] = *(const PG8_LAS bf16x8*)(lds + PG8_SA(b, h) + aoff + m * 2048 + k * 1024); } while (0)
; #define PG8_MMA(ai, bj, At, Bt) do { __builtin_amdgcn_s_setprio(1); _Pragma("unroll") for (int m = 0; m < 4; ++m) _Pragma("unroll") for (int n = 0; n < 2; ++n) _Pragma("unroll") for (int k = 0; k < 2; ++k) \
;         acc[ai][bj][m][n] = __builtin_amdgcn_mfma_f32_16x16x32_bf16(Bt[n][k], At[m][k], acc[ai][bj][m][n], 0, 0, 0); __builtin_amdgcn_s_setprio(0); } while (0)
; #define PG8_WAIT_V(n) asm volatile("s_waitcnt vmcnt(" #n ")" ::: "memory")
; #define PG8_WAIT_L(n) asm volatile("s_waitcnt lgkmcnt(" #n ")" ::: "memory")
; #define PG8_BAR __builtin_amdgcn_s_barrier()
; #define PG8_SCHED __builtin_amdgcn_sched_barrier(0)
; template <class Epi, class Sched, bool ALIGN_EPI = false, bool SP2 = false>
; __device__ __forceinline__ void gemm_phase(PG8_LAS unsigned char* lds, const Gemm g, const Sched& S, const Epi& E, const int wave_in) {
;     ...
;         for (int t = 0; t < nt; t += 2) {
;             const bool last = (t == nt - 2);
;     ...
;             PG8_LDA(At, 1, 1); PG8_STAGE(PG8_SB(1, 0), b3, voffB); PG8_STAGE(PG8_SB(1, 1), b3 + hstepB, voffB); PG8_STAGE(PG8_SA(1, 0), a3, voffA);
;             PG8_WAIT_V(8); PG8_WAIT_L(0); PG8_BAR; PG8_MMA(1, 0, At, B0); PG8_MMA(1, 1, At, B1); PG8_BAR; PG8_SCHED;
	s_add_i32 s30, s62, s38
	v_lshl_add_u64 v[210:211], v[210:211], 0, s[6:7]
	s_mov_b32 m0, s30
	ds_read_b128 v[178:181], v216 offset:49152
	ds_read_b128 v[182:185], v216 offset:50176
	ds_read_b128 v[186:189], v216 offset:51200
	ds_read_b128 v[190:193], v216 offset:52224
	ds_read_b128 v[194:197], v216 offset:53248
	ds_read_b128 v[198:201], v216 offset:54272
	ds_read_b128 v[202:205], v216 offset:55296
	ds_read_b128 v[206:209], v216 offset:56320
	global_load_lds_dwordx4 v[210:211], off
	s_add_i32 m0, s30, 0x2000
	s_add_u32 s28, s28, 0x80080
	v_lshl_add_u64 v[210:211], v[218:219], 0, s[6:7]
	s_addc_u32 s29, s29, 0
	s_add_i32 s30, s63, s38
	global_load_lds_dwordx4 v[210:211], off
	v_lshl_add_u64 v[210:211], s[28:29], 0, v[148:149]
	s_mov_b32 m0, s30
	s_nop 0
	global_load_lds_dwordx4 v[210:211], off
	v_lshl_add_u64 v[210:211], s[28:29], 0, v[144:145]
	s_add_i32 m0, s30, 0x2000
	s_nop 0
	global_load_lds_dwordx4 v[210:211], off
	v_lshl_add_u64 v[210:211], v[220:221], 0, s[6:7]
	s_mov_b32 m0, s48
	s_nop 0
	global_load_lds_dwordx4 v[210:211], off
	v_lshl_add_u64 v[210:211], v[222:223], 0, s[6:7]
	s_mov_b32 m0, s49
	s_nop 0
	global_load_lds_dwordx4 v[210:211], off
	s_waitcnt vmcnt(8)
	s_waitcnt lgkmcnt(0)
	s_barrier
	s_setprio 1
	s_waitcnt lgkmcnt(0)
	v_mfma_f32_16x16x32_bf16 v[60:63], v[128:131], v[178:181], v[60:63]
	v_mfma_f32_16x16x32_bf16 v[56:59], v[136:139], v[178:181], v[56:59]
	v_mfma_f32_16x16x32_bf16 v[48:51], v[128:131], v[186:189], v[48:51]
	v_mfma_f32_16x16x32_bf16 v[40:43], v[136:139], v[186:189], v[40:43]
	v_mfma_f32_16x16x32_bf16 v[32:35], v[128:131], v[194:197], v[32:35]
	v_mfma_f32_16x16x32_bf16 v[24:27], v[136:139], v[194:197], v[24:27]
	v_mfma_f32_16x16x32_bf16 v[16:19], v[128:131], v[202:205], v[16:19]
	v_mfma_f32_16x16x32_bf16 v[8:11], v[136:139], v[202:205], v[8:11]
	v_mfma_f32_16x16x32_bf16 v[60:63], v[132:135], v[182:185], v[60:63]
	v_mfma_f32_16x16x32_bf16 v[56:59], v[140:143], v[182:185], v[56:59]
	v_mfma_f32_16x16x32_bf16 v[48:51], v[132:135], v[190:193], v[48:51]
	v_mfma_f32_16x16x32_bf16 v[40:43], v[140:143], v[190:193], v[40:43]
	v_mfma_f32_16x16x32_bf16 v[32:35], v[132:135], v[198:201], v[32:35]
	v_mfma_f32_16x16x32_bf16 v[24:27], v[140:143], v[198:201], v[24:27]
	v_mfma_f32_16x16x32_bf16 v[16:19], v[132:135], v[206:209], v[16:19]
	v_mfma_f32_16x16x32_bf16 v[8:11], v[140:143], v[206:209], v[8:11]
	s_setprio 0
	s_setprio 1
	v_mfma_f32_16x16x32_bf16 v[52:55], v[162:165], v[178:181], v[52:55]
	v_mfma_f32_16x16x32_bf16 v[44:47], v[170:173], v[178:181], v[44:47]
	v_mfma_f32_16x16x32_bf16 v[36:39], v[162:165], v[186:189], v[36:39]
	v_mfma_f32_16x16x32_bf16 v[28:31], v[170:173], v[186:189], v[28:31]
	v_mfma_f32_16x16x32_bf16 v[20:23], v[162:165], v[194:197], v[20:23]
	v_mfma_f32_16x16x32_bf16 v[12:15], v[170:173], v[194:197], v[12:15]
	v_mfma_f32_16x16x32_bf16 v[4:7], v[162:165], v[202:205], v[4:7]
	v_mfma_f32_16x16x32_bf16 v[0:3], v[170:173], v[202:205], v[0:3]
	v_mfma_f32_16x16x32_bf16 v[52:55], v[166:169], v[182:185], v[52:55]
	v_mfma_f32_16x16x32_bf16 v[44:47], v[174:177], v[182:185], v[44:47]
	v_mfma_f32_16x16x32_bf16 v[36:39], v[166:169], v[190:193], v[36:39]
	v_mfma_f32_16x16x32_bf16 v[28:31], v[174:177], v[190:193], v[28:31]
	v_mfma_f32_16x16x32_bf16 v[20:23], v[166:169], v[198:201], v[20:23]
	v_mfma_f32_16x16x32_bf16 v[12:15], v[174:177], v[198:201], v[12:15]
	v_mfma_f32_16x16x32_bf16 v[4:7], v[166:169], v[206:209], v[4:7]
	v_mfma_f32_16x16x32_bf16 v[0:3], v[174:177], v[206:209], v[0:3]
	s_setprio 0
	s_add_i32 s61, s61, 2
	s_add_u32 s26, s26, 0x100
	s_addc_u32 s27, s27, 0
	s_add_u32 s59, s59, 0x100
	s_addc_u32 s60, s60, 0
	s_cmp_gt_u32 s61, 29
	s_barrier
	s_cbranch_scc0 .LBB0_1825
	s_and_b64 vcc, exec, s[8:9]
	s_cbranch_vccz .LBB0_1828
	s_barrier

; #define PG8_STAGE(bufoff, gbase, voff) do { _Pragma("unroll") for (int _i = 0; _i < 2; ++_i) \
;         __builtin_amdgcn_global_load_lds((const unsigned*)((const char*)(gbase) + (voff)[_i]), (PG8_LAS unsigned*)(lds + (bufoff) + ldsw + _i * 8192), 16, 0, 0); } while (0)
; #define PG8_LDA(dst, b, h) do { _Pragma("unroll") for (int m = 0; m < 4; ++m) _Pragma("unroll") for (int k = 0; k < 2; ++k) dst[m][k] = *(const PG8_LAS bf16x8*)(lds + PG8_SA(b, h) + aoff + m * 2048 + k * 1024); } while (0)
; #define PG8_LDB(dst, b, h) do { _Pragma("unroll") for (int n = 0; n < 2; ++n) _Pragma("unroll") for (int k = 0; k < 2; ++k) dst[n][k] = *(const PG8_LAS bf16x8*)(lds + PG8_SB(b, h) + boff + n * 2048 + k * 1024); } while (0)
; #define PG8_MMA(ai, bj, At, Bt) do { __builtin_amdgcn_s_setprio(1); _Pragma("unroll") for (int m = 0; m < 4; ++m) _Pragma("unroll") for (int n = 0; n < 2; ++n) _Pragma("unroll") for (int k = 0; k < 2; ++k) \
;         acc[ai][bj][m][n] = __builtin_amdgcn_mfma_f32_16x16x32_bf16(Bt[n][k], At[m][k], acc[ai][bj][m][n], 0, 0, 0); __builtin_amdgcn_s_setprio(0); } while (0)
; #define PG8_WAIT_V(n) asm volatile("s_waitcnt vmcnt(" #n ")" ::: "memory")
; #define PG8_WAIT_L(n) asm volatile("s_waitcnt lgkmcnt(" #n ")" ::: "memory")
; #define PG8_BAR __builtin_amdgcn_s_barrier()
; template <class Epi, class Sched, bool ALIGN_EPI = false, bool SP2 = false>
; __device__ __forceinline__ void gemm_phase(PG8_LAS unsigned char* lds, const Gemm g, const Sched& S, const Epi& E, const int wave_in) {
;     ...
;         for (int t = 0; t < nt; t += 2) {
;             const bool last = (t == nt - 2);
;             const char* a1 = cA + (size_t)(t + 1) * kstep;
;             const char* a2 = last ? nA : cA + (size_t)(t + 2) * kstep; const char* b2 = last ? nB : cB + (size_t)(t + 2) * kstep;
;             const char* a3 = a2 + kstep; const char* b3 = b2 + kstep;
;             if (last && has_next) S.a_ready(nxt);
;             if constexpr (SP2) {
;             PG8_LDB(B0, 0, 0); PG8_LDB(B1, 0, 1); PG8_SCHED; PG8_LDA(At, 0, 0); PG8_STAGE(PG8_SA(1, 1), a1 + hstepA, voffA);
;             PG8_WAIT_V(8); PG8_WAIT_L(0); PG8_BAR; PG8_MMA(0, 0, At, B0); PG8_MMA(0, 1, At, B1); PG8_BAR; PG8_SCHED;
;             PG8_LDA(At, 0, 1); PG8_STAGE(PG8_SB(0, 0), b2, voffB); PG8_STAGE(PG8_SB(0, 1), b2 + hstepB, voffB); PG8_STAGE(PG8_SA(0, 0), a2, voffA);
.LBB0_2248:
	ds_read_b128 v[144:147], v151
	ds_read_b128 v[154:157], v151 offset:1024
	ds_read_b128 v[158:161], v151 offset:2048
	ds_read_b128 v[162:165], v151 offset:3072
	ds_read_b128 v[166:169], v152
	ds_read_b128 v[170:173], v152 offset:1024
	ds_read_b128 v[174:177], v152 offset:2048
	ds_read_b128 v[178:181], v152 offset:3072
	s_add_u32 s24, s22, 0xfff80080
	s_addc_u32 s25, s23, -1
	s_cmp_eq_u32 s50, 28
	s_cselect_b32 s27, s5, s25
	s_cselect_b32 s26, s15, s24
	s_cselect_b32 s25, s13, s49
	s_cselect_b32 s24, s47, s48
	v_lshl_add_u64 v[214:215], s[22:23], 0, v[136:137]
	s_add_i32 m0, s21, 0xc000
	ds_read_b128 v[182:185], v153
	ds_read_b128 v[186:189], v153 offset:1024
	ds_read_b128 v[190:193], v153 offset:2048
	ds_read_b128 v[194:197], v153 offset:3072
	ds_read_b128 v[198:201], v153 offset:4096
	ds_read_b128 v[202:205], v153 offset:5120
	ds_read_b128 v[206:209], v153 offset:6144
	ds_read_b128 v[210:213], v153 offset:7168
	global_load_lds_dwordx4 v[214:215], off
	v_lshl_add_u64 v[214:215], s[22:23], 0, v[138:139]
	s_add_i32 m0, s21, 0xe000
	s_nop 0
	global_load_lds_dwordx4 v[214:215], off
	s_waitcnt vmcnt(8)
	s_waitcnt lgkmcnt(0)
	s_barrier
	s_setprio 1
	s_waitcnt lgkmcnt(0)
	v_mfma_f32_16x16x32_bf16 v[124:127], v[144:147], v[182:185], v[124:127]
	v_mfma_f32_16x16x32_bf16 v[120:123], v[158:161], v[182:185], v[120:123]
	v_mfma_f32_16x16x32_bf16 v[108:111], v[144:147], v[190:193], v[108:111]
	v_mfma_f32_16x16x32_bf16 v[104:107], v[158:161], v[190:193], v[104:107]
	v_mfma_f32_16x16x32_bf16 v[92:95], v[144:147], v[198:201], v[92:95]
	v_mfma_f32_16x16x32_bf16 v[88:91], v[158:161], v[198:201], v[88:91]
	v_mfma_f32_16x16x32_bf16 v[76:79], v[144:147], v[206:209], v[76:79]
	v_mfma_f32_16x16x32_bf16 v[72:75], v[158:161], v[206:209], v[72:75]
	v_mfma_f32_16x16x32_bf16 v[124:127], v[154:157], v[186:189], v[124:127]
	v_mfma_f32_16x16x32_bf16 v[120:123], v[162:165], v[186:189], v[120:123]
	v_mfma_f32_16x16x32_bf16 v[108:111], v[154:157], v[194:197], v[108:111]
	v_mfma_f32_16x16x32_bf16 v[104:107], v[162:165], v[194:197], v[104:107]
	v_mfma_f32_16x16x32_bf16 v[92:95], v[154:157], v[202:205], v[92:95]
	v_mfma_f32_16x16x32_bf16 v[88:91], v[162:165], v[202:205], v[88:91]
	v_mfma_f32_16x16x32_bf16 v[76:79], v[154:157], v[210:213], v[76:79]
	v_mfma_f32_16x16x32_bf16 v[72:75], v[162:165], v[210:213], v[72:75]
	s_setprio 0
	s_setprio 1
	v_mfma_f32_16x16x32_bf16 v[116:119], v[166:169], v[182:185], v[116:119]
	v_mfma_f32_16x16x32_bf16 v[112:115], v[174:177], v[182:185], v[112:115]
	v_mfma_f32_16x16x32_bf16 v[100:103], v[166:169], v[190:193], v[100:103]
	v_mfma_f32_16x16x32_bf16 v[96:99], v[174:177], v[190:193], v[96:99]
	v_mfma_f32_16x16x32_bf16 v[84:87], v[166:169], v[198:201], v[84:87]
	v_mfma_f32_16x16x32_bf16 v[80:83], v[174:177], v[198:201], v[80:83]
	v_mfma_f32_16x16x32_bf16 v[68:71], v[166:169], v[206:209], v[68:71]
	v_mfma_f32_16x16x32_bf16 v[64:67], v[174:177], v[206:209], v[64:67]
	v_mfma_f32_16x16x32_bf16 v[116:119], v[170:173], v[186:189], v[116:119]
	v_mfma_f32_16x16x32_bf16 v[112:115], v[178:181], v[186:189], v[112:115]
	v_mfma_f32_16x16x32_bf16 v[100:103], v[170:173], v[194:197], v[100:103]
	v_mfma_f32_16x16x32_bf16 v[96:99], v[178:181], v[194:197], v[96:99]
	v_mfma_f32_16x16x32_bf16 v[84:87], v[170:173], v[202:205], v[84:87]
	v_mfma_f32_16x16x32_bf16 v[80:83], v[178:181], v[202:205], v[80:83]
	v_mfma_f32_16x16x32_bf16 v[68:71], v[170:173], v[210:213], v[68:71]
	v_mfma_f32_16x16x32_bf16 v[64:67], v[178:181], v[210:213], v[64:67]
	s_setprio 0
	s_barrier
	s_add_i32 s51, s44, s34
	v_lshl_add_u64 v[214:215], s[24:25], 0, v[130:131]
	s_mov_b32 m0, s51
	ds_read_b128 v[182:185], v153 offset:16384
	ds_read_b128 v[186:189], v153 offset:17408
	ds_read_b128 v[190:193], v153 offset:18432
	ds_read_b128 v[194:197], v153 offset:19456
	ds_read_b128 v[198:201], v153 offset:20480
	ds_read_b128 v[202:205], v153 offset:21504
	ds_read_b128 v[206:209], v153 offset:22528
	ds_read_b128 v[210:213], v153 offset:23552
	global_load_lds_dwordx4 v[214:215], off
	s_add_i32 m0, s51, 0x2000
	s_add_u32 s52, s24, 0x80000
	v_lshl_add_u64 v[216:217], s[24:25], 0, v[134:135]
	s_addc_u32 s53, s25, 0
	s_add_i32 s51, s45, s34
	global_load_lds_dwordx4 v[216:217], off
	v_lshl_add_u64 v[218:219], s[52:53], 0, v[130:131]
	s_mov_b32 m0, s51
	v_lshl_add_u64 v[220:221], s[26:27], 0, v[132:133]
	global_load_lds_dwordx4 v[218:219], off
	v_lshl_add_u64 v[218:219], s[52:53], 0, v[134:135]
	s_add_i32 m0, s51, 0x2000
	s_nop 0
	global_load_lds_dwordx4 v[218:219], off
	v_lshl_add_u64 v[218:219], s[26:27], 0, v[128:129]
	s_mov_b32 m0, s21
	s_nop 0
	global_load_lds_dwordx4 v[218:219], off
	s_mov_b32 m0, s35
	s_nop 0
	global_load_lds_dwordx4 v[220:221], off
	s_waitcnt vmcnt(8)
	s_waitcnt lgkmcnt(0)
	s_barrier
; #define PG8_STAGE(bufoff, gbase, voff) do { _Pragma("unroll") for (int _i = 0; _i < 2; ++_i) \
;         __builtin_amdgcn_global_load_lds((const unsigned*)((const char*)(gbase) + (voff)[_i]), (PG8_LAS unsigned*)(lds + (bufoff) + ldsw + _i * 8192), 16, 0, 0); } while (0)
; #define PG8_LDA(dst, b, h) do { _Pragma("unroll") for (int m = 0; m < 4; ++m) _Pragma("unroll") for (int k = 0; k < 2; ++k) dst[m][k] = *(const PG8_LAS bf16x8*)(lds + PG8_SA(b, h) + aoff + m * 2048 + k * 1024); } while (0)
; #define PG8_LDB(dst, b, h) do { _Pragma("unroll") for (int n = 0; n < 2; ++n) _Pragma("unroll") for (int k = 0; k < 2; ++k) dst[n][k] = *(const PG8_LAS bf16x8*)(lds + PG8_SB(b, h) + boff + n * 2048 + k * 1024); } while (0)
; #define PG8_MMA(ai, bj, At, Bt) do { __builtin_amdgcn_s_setprio(1); _Pragma("unroll") for (int m = 0; m < 4; ++m) _Pragma("unroll") for (int n = 0; n < 2; ++n) _Pragma("unroll") for (int k = 0; k < 2; ++k) \
;         acc[ai][bj][m][n] = __builtin_amdgcn_mfma_f32_16x16x32_bf16(Bt[n][k], At[m][k], acc[ai][bj][m][n], 0, 0, 0); __builtin_amdgcn_s_setprio(0); } while (0)
; #define PG8_WAIT_V(n) asm volatile("s_waitcnt vmcnt(" #n ")" ::: "memory")
; #define PG8_WAIT_L(n) asm volatile("s_waitcnt lgkmcnt(" #n ")" ::: "memory")
; #define PG8_BAR __builtin_amdgcn_s_barrier()
; #define PG8_SCHED __builtin_amdgcn_sched_barrier(0)
; template <class Epi, class Sched, bool ALIGN_EPI = false, bool SP2 = false>
; __device__ __forceinline__ void gemm_phase(PG8_LAS unsigned char* lds, const Gemm g, const Sched& S, const Epi& E, const int wave_in) {
;     ...
;             PG8_WAIT_V(8); PG8_WAIT_L(0); PG8_BAR; PG8_MMA(1, 0, At, B0); PG8_MMA(1, 1, At, B1); PG8_BAR; PG8_SCHED;
;             PG8_LDB(B0, 1, 0); PG8_LDB(B1, 1, 1); PG8_SCHED; PG8_LDA(At, 1, 0); PG8_STAGE(PG8_SA(0, 1), a2 + hstepA, voffA);
;             PG8_WAIT_V(8); PG8_WAIT_L(0); PG8_BAR; PG8_MMA(0, 0, At, B0); PG8_MMA(0, 1, At, B1); PG8_BAR; PG8_SCHED;
	s_setprio 1
	s_waitcnt lgkmcnt(0)
	v_mfma_f32_16x16x32_bf16 v[60:63], v[144:147], v[182:185], v[60:63]
	v_mfma_f32_16x16x32_bf16 v[56:59], v[158:161], v[182:185], v[56:59]
	v_mfma_f32_16x16x32_bf16 v[44:47], v[144:147], v[190:193], v[44:47]
	v_mfma_f32_16x16x32_bf16 v[40:43], v[158:161], v[190:193], v[40:43]
	v_mfma_f32_16x16x32_bf16 v[28:31], v[144:147], v[198:201], v[28:31]
	v_mfma_f32_16x16x32_bf16 v[24:27], v[158:161], v[198:201], v[24:27]
	v_mfma_f32_16x16x32_bf16 v[12:15], v[144:147], v[206:209], v[12:15]
	v_mfma_f32_16x16x32_bf16 v[8:11], v[158:161], v[206:209], v[8:11]
	v_mfma_f32_16x16x32_bf16 v[60:63], v[154:157], v[186:189], v[60:63]
	v_mfma_f32_16x16x32_bf16 v[56:59], v[162:165], v[186:189], v[56:59]
	v_mfma_f32_16x16x32_bf16 v[44:47], v[154:157], v[194:197], v[44:47]
	v_mfma_f32_16x16x32_bf16 v[40:43], v[162:165], v[194:197], v[40:43]
	v_mfma_f32_16x16x32_bf16 v[28:31], v[154:157], v[202:205], v[28:31]
	v_mfma_f32_16x16x32_bf16 v[24:27], v[162:165], v[202:205], v[24:27]
	v_mfma_f32_16x16x32_bf16 v[12:15], v[154:157], v[210:213], v[12:15]
	v_mfma_f32_16x16x32_bf16 v[8:11], v[162:165], v[210:213], v[8:11]
	s_setprio 0
	s_setprio 1
	v_mfma_f32_16x16x32_bf16 v[52:55], v[166:169], v[182:185], v[52:55]
	v_mfma_f32_16x16x32_bf16 v[48:51], v[174:177], v[182:185], v[48:51]
	v_mfma_f32_16x16x32_bf16 v[36:39], v[166:169], v[190:193], v[36:39]
	v_mfma_f32_16x16x32_bf16 v[32:35], v[174:177], v[190:193], v[32:35]
	v_mfma_f32_16x16x32_bf16 v[20:23], v[166:169], v[198:201], v[20:23]
	v_mfma_f32_16x16x32_bf16 v[16:19], v[174:177], v[198:201], v[16:19]
	v_mfma_f32_16x16x32_bf16 v[4:7], v[166:169], v[206:209], v[4:7]
	v_mfma_f32_16x16x32_bf16 v[0:3], v[174:177], v[206:209], v[0:3]
	v_mfma_f32_16x16x32_bf16 v[52:55], v[170:173], v[186:189], v[52:55]
	v_mfma_f32_16x16x32_bf16 v[48:51], v[178:181], v[186:189], v[48:51]
	v_mfma_f32_16x16x32_bf16 v[36:39], v[170:173], v[194:197], v[36:39]
	v_mfma_f32_16x16x32_bf16 v[32:35], v[178:181], v[194:197], v[32:35]
	v_mfma_f32_16x16x32_bf16 v[20:23], v[170:173], v[202:205], v[20:23]
	v_mfma_f32_16x16x32_bf16 v[16:19], v[178:181], v[202:205], v[16:19]
	v_mfma_f32_16x16x32_bf16 v[4:7], v[170:173], v[210:213], v[4:7]
	v_mfma_f32_16x16x32_bf16 v[0:3], v[178:181], v[210:213], v[0:3]
	s_setprio 0
	s_barrier
	s_add_i32 s51, 0, 0x18000
	s_add_i32 s52, 0, 0x1c000
	v_add_u32_e32 v162, s51, v149
	v_add_u32_e32 v178, s52, v149
	ds_read_b128 v[144:147], v162
	ds_read_b128 v[154:157], v162 offset:1024
	ds_read_b128 v[158:161], v162 offset:2048
	ds_read_b128 v[162:165], v162 offset:3072
	ds_read_b128 v[166:169], v178
	ds_read_b128 v[170:173], v178 offset:1024
	ds_read_b128 v[174:177], v178 offset:2048
	ds_read_b128 v[178:181], v178 offset:3072
	s_add_u32 s26, s26, 0x80000
	s_addc_u32 s27, s27, 0
	s_mov_b32 m0, s36
	v_lshl_add_u64 v[222:223], s[26:27], 0, v[128:129]
	ds_read_b128 v[182:185], v153 offset:32768
	ds_read_b128 v[186:189], v153 offset:33792
	ds_read_b128 v[190:193], v153 offset:34816
	ds_read_b128 v[194:197], v153 offset:35840
	ds_read_b128 v[198:201], v153 offset:36864
	ds_read_b128 v[202:205], v153 offset:37888
	ds_read_b128 v[206:209], v153 offset:38912
	ds_read_b128 v[210:213], v153 offset:39936
	global_load_lds_dwordx4 v[222:223], off
	v_lshl_add_u64 v[222:223], s[26:27], 0, v[132:133]
	s_mov_b32 m0, s37
	s_nop 0
	global_load_lds_dwordx4 v[222:223], off
	s_waitcnt vmcnt(8)
	s_waitcnt lgkmcnt(0)
	s_barrier
	s_setprio 1
	s_waitcnt lgkmcnt(0)
	v_mfma_f32_16x16x32_bf16 v[124:127], v[144:147], v[182:185], v[124:127]
	v_mfma_f32_16x16x32_bf16 v[120:123], v[158:161], v[182:185], v[120:123]
	v_mfma_f32_16x16x32_bf16 v[108:111], v[144:147], v[190:193], v[108:111]
	v_mfma_f32_16x16x32_bf16 v[104:107], v[158:161], v[190:193], v[104:107]
	v_mfma_f32_16x16x32_bf16 v[92:95], v[144:147], v[198:201], v[92:95]
	v_mfma_f32_16x16x32_bf16 v[88:91], v[158:161], v[198:201], v[88:91]
	v_mfma_f32_16x16x32_bf16 v[76:79], v[144:147], v[206:209], v[76:79]
	v_mfma_f32_16x16x32_bf16 v[72:75], v[158:161], v[206:209], v[72:75]
	v_mfma_f32_16x16x32_bf16 v[124:127], v[154:157], v[186:189], v[124:127]
	v_mfma_f32_16x16x32_bf16 v[120:123], v[162:165], v[186:189], v[120:123]
	v_mfma_f32_16x16x32_bf16 v[108:111], v[154:157], v[194:197], v[108:111]
	v_mfma_f32_16x16x32_bf16 v[104:107], v[162:165], v[194:197], v[104:107]
	v_mfma_f32_16x16x32_bf16 v[92:95], v[154:157], v[202:205], v[92:95]
	v_mfma_f32_16x16x32_bf16 v[88:91], v[162:165], v[202:205], v[88:91]
	v_mfma_f32_16x16x32_bf16 v[76:79], v[154:157], v[210:213], v[76:79]
	v_mfma_f32_16x16x32_bf16 v[72:75], v[162:165], v[210:213], v[72:75]
	s_setprio 0
	s_setprio 1
	v_mfma_f32_16x16x32_bf16 v[116:119], v[166:169], v[182:185], v[116:119]
	v_mfma_f32_16x16x32_bf16 v[112:115], v[174:177], v[182:185], v[112:115]
	v_mfma_f32_16x16x32_bf16 v[100:103], v[166:169], v[190:193], v[100:103]
	v_mfma_f32_16x16x32_bf16 v[96:99], v[174:177], v[190:193], v[96:99]
	v_mfma_f32_16x16x32_bf16 v[84:87], v[166:169], v[198:201], v[84:87]
	v_mfma_f32_16x16x32_bf16 v[80:83], v[174:177], v[198:201], v[80:83]
	v_mfma_f32_16x16x32_bf16 v[68:71], v[166:169], v[206:209], v[68:71]
	v_mfma_f32_16x16x32_bf16 v[64:67], v[174:177], v[206:209], v[64:67]
	v_mfma_f32_16x16x32_bf16 v[116:119], v[170:173], v[186:189], v[116:119]
	v_mfma_f32_16x16x32_bf16 v[112:115], v[178:181], v[186:189], v[112:115]
	v_mfma_f32_16x16x32_bf16 v[100:103], v[170:173], v[194:197], v[100:103]
	v_mfma_f32_16x16x32_bf16 v[96:99], v[178:181], v[194:197], v[96:99]
	v_mfma_f32_16x16x32_bf16 v[84:87], v[170:173], v[202:205], v[84:87]
	v_mfma_f32_16x16x32_bf16 v[80:83], v[178:181], v[202:205], v[80:83]
	v_mfma_f32_16x16x32_bf16 v[68:71], v[170:173], v[210:213], v[68:71]
	v_mfma_f32_16x16x32_bf16 v[64:67], v[178:181], v[210:213], v[64:67]
	s_setprio 0
	s_barrier
; #define PG8_STAGE(bufoff, gbase, voff) do { _Pragma("unroll") for (int _i = 0; _i < 2; ++_i) \
;         __builtin_amdgcn_global_load_lds((const unsigned*)((const char*)(gbase) + (voff)[_i]), (PG8_LAS unsigned*)(lds + (bufoff) + ldsw + _i * 8192), 16, 0, 0); } while (0)
; #define PG8_LDA(dst, b, h) do { _Pragma("unroll") for (int m = 0; m < 4; ++m) _Pragma("unroll") for (int k = 0; k < 2; ++k) dst[m][k] = *(const PG8_LAS bf16x8*)(lds + PG8_SA(b, h) + aoff + m * 2048 + k * 1024); } while (0)
; #define PG8_MMA(ai, bj, At, Bt) do { __builtin_amdgcn_s_setprio(1); _Pragma("unroll") for (int m = 0; m < 4; ++m) _Pragma("unroll") for (int n = 0; n < 2; ++n) _Pragma("unroll") for (int k = 0; k < 2; ++k) \
;         acc[ai][bj][m][n] = __builtin_amdgcn_mfma_f32_16x16x32_bf16(Bt[n][k], At[m][k], acc[ai][bj][m][n], 0, 0, 0); __builtin_amdgcn_s_setprio(0); } while (0)
; #define PG8_WAIT_V(n) asm volatile("s_waitcnt vmcnt(" #n ")" ::: "memory")
; #define PG8_WAIT_L(n) asm volatile("s_waitcnt lgkmcnt(" #n ")" ::: "memory")
; #define PG8_BAR __builtin_amdgcn_s_barrier()
; #define PG8_SCHED __builtin_amdgcn_sched_barrier(0)
; template <class Epi, class Sched, bool ALIGN_EPI = false, bool SP2 = false>
; __device__ __forceinline__ void gemm_phase(PG8_LAS unsigned char* lds, const Gemm g, const Sched& S, const Epi& E, const int wave_in) {
;     ...
;         for (int t = 0; t < nt; t += 2) {
;             const bool last = (t == nt - 2);
;     ...
;             PG8_LDA(At, 1, 1); PG8_STAGE(PG8_SB(1, 0), b3, voffB); PG8_STAGE(PG8_SB(1, 1), b3 + hstepB, voffB); PG8_STAGE(PG8_SA(1, 0), a3, voffA);
;             PG8_WAIT_V(8); PG8_WAIT_L(0); PG8_BAR; PG8_MMA(1, 0, At, B0); PG8_MMA(1, 1, At, B1); PG8_BAR; PG8_SCHED;
	s_add_i32 s26, s51, s34
	v_lshl_add_u64 v[214:215], v[214:215], 0, s[8:9]
	s_mov_b32 m0, s26
	ds_read_b128 v[182:185], v153 offset:49152
	ds_read_b128 v[186:189], v153 offset:50176
	ds_read_b128 v[190:193], v153 offset:51200
	ds_read_b128 v[194:197], v153 offset:52224
	ds_read_b128 v[198:201], v153 offset:53248
	ds_read_b128 v[202:205], v153 offset:54272
	ds_read_b128 v[206:209], v153 offset:55296
	ds_read_b128 v[210:213], v153 offset:56320
	global_load_lds_dwordx4 v[214:215], off
	s_add_i32 m0, s26, 0x2000
	s_add_u32 s24, s24, 0x80080
	v_lshl_add_u64 v[214:215], v[216:217], 0, s[8:9]
	s_addc_u32 s25, s25, 0
	s_add_i32 s26, s52, s34
	global_load_lds_dwordx4 v[214:215], off
	v_lshl_add_u64 v[214:215], s[24:25], 0, v[130:131]
	s_mov_b32 m0, s26
	s_nop 0
	global_load_lds_dwordx4 v[214:215], off
	v_lshl_add_u64 v[214:215], s[24:25], 0, v[134:135]
	s_add_i32 m0, s26, 0x2000
	s_nop 0
	global_load_lds_dwordx4 v[214:215], off
	v_lshl_add_u64 v[214:215], v[218:219], 0, s[8:9]
	s_mov_b32 m0, s39
	s_nop 0
	global_load_lds_dwordx4 v[214:215], off
	v_lshl_add_u64 v[214:215], v[220:221], 0, s[8:9]
	s_mov_b32 m0, s40
	s_nop 0
	global_load_lds_dwordx4 v[214:215], off
	s_waitcnt vmcnt(8)
	s_waitcnt lgkmcnt(0)
	s_barrier
	s_setprio 1
	s_waitcnt lgkmcnt(0)
	v_mfma_f32_16x16x32_bf16 v[60:63], v[144:147], v[182:185], v[60:63]
	v_mfma_f32_16x16x32_bf16 v[56:59], v[158:161], v[182:185], v[56:59]
	v_mfma_f32_16x16x32_bf16 v[44:47], v[144:147], v[190:193], v[44:47]
	v_mfma_f32_16x16x32_bf16 v[40:43], v[158:161], v[190:193], v[40:43]
	v_mfma_f32_16x16x32_bf16 v[28:31], v[144:147], v[198:201], v[28:31]
	v_mfma_f32_16x16x32_bf16 v[24:27], v[158:161], v[198:201], v[24:27]
	v_mfma_f32_16x16x32_bf16 v[12:15], v[144:147], v[206:209], v[12:15]
	v_mfma_f32_16x16x32_bf16 v[8:11], v[158:161], v[206:209], v[8:11]
	v_mfma_f32_16x16x32_bf16 v[60:63], v[154:157], v[186:189], v[60:63]
	v_mfma_f32_16x16x32_bf16 v[56:59], v[162:165], v[186:189], v[56:59]
	v_mfma_f32_16x16x32_bf16 v[44:47], v[154:157], v[194:197], v[44:47]
	v_mfma_f32_16x16x32_bf16 v[40:43], v[162:165], v[194:197], v[40:43]
	v_mfma_f32_16x16x32_bf16 v[28:31], v[154:157], v[202:205], v[28:31]
	v_mfma_f32_16x16x32_bf16 v[24:27], v[162:165], v[202:205], v[24:27]
	v_mfma_f32_16x16x32_bf16 v[12:15], v[154:157], v[210:213], v[12:15]
	v_mfma_f32_16x16x32_bf16 v[8:11], v[162:165], v[210:213], v[8:11]
	s_setprio 0
	s_setprio 1
	v_mfma_f32_16x16x32_bf16 v[52:55], v[166:169], v[182:185], v[52:55]
	v_mfma_f32_16x16x32_bf16 v[48:51], v[174:177], v[182:185], v[48:51]
	v_mfma_f32_16x16x32_bf16 v[36:39], v[166:169], v[190:193], v[36:39]
	v_mfma_f32_16x16x32_bf16 v[32:35], v[174:177], v[190:193], v[32:35]
	v_mfma_f32_16x16x32_bf16 v[20:23], v[166:169], v[198:201], v[20:23]
	v_mfma_f32_16x16x32_bf16 v[16:19], v[174:177], v[198:201], v[16:19]
	v_mfma_f32_16x16x32_bf16 v[4:7], v[166:169], v[206:209], v[4:7]
	v_mfma_f32_16x16x32_bf16 v[0:3], v[174:177], v[206:209], v[0:3]
	v_mfma_f32_16x16x32_bf16 v[52:55], v[170:173], v[186:189], v[52:55]
	v_mfma_f32_16x16x32_bf16 v[48:51], v[178:181], v[186:189], v[48:51]
	v_mfma_f32_16x16x32_bf16 v[36:39], v[170:173], v[194:197], v[36:39]
	v_mfma_f32_16x16x32_bf16 v[32:35], v[178:181], v[194:197], v[32:35]
	v_mfma_f32_16x16x32_bf16 v[20:23], v[170:173], v[202:205], v[20:23]
	v_mfma_f32_16x16x32_bf16 v[16:19], v[178:181], v[202:205], v[16:19]
	v_mfma_f32_16x16x32_bf16 v[4:7], v[170:173], v[210:213], v[4:7]
	v_mfma_f32_16x16x32_bf16 v[0:3], v[178:181], v[210:213], v[0:3]
	s_setprio 0
	s_add_i32 s50, s50, 2
	s_add_u32 s22, s22, 0x100
	s_addc_u32 s23, s23, 0
	s_add_u32 s48, s48, 0x100
	s_addc_u32 s49, s49, 0
	s_cmp_gt_u32 s50, 29
	s_barrier
	s_cbranch_scc0 .LBB0_2248
	s_and_b64 vcc, exec, s[10:11]
	s_cbranch_vccz .LBB0_2251
	s_barrier

; #define PG8_STAGE(bufoff, gbase, voff) do { _Pragma("unroll") for (int _i = 0; _i < 2; ++_i) \
;         __builtin_amdgcn_global_load_lds((const unsigned*)((const char*)(gbase) + (voff)[_i]), (PG8_LAS unsigned*)(lds + (bufoff) + ldsw + _i * 8192), 16, 0, 0); } while (0)
; #define PG8_LDA(dst, b, h) do { _Pragma("unroll") for (int m = 0; m < 4; ++m) _Pragma("unroll") for (int k = 0; k < 2; ++k) dst[m][k] = *(const PG8_LAS bf16x8*)(lds + PG8_SA(b, h) + aoff + m * 2048 + k * 1024); } while (0)
; #define PG8_LDB(dst, b, h) do { _Pragma("unroll") for (int n = 0; n < 2; ++n) _Pragma("unroll") for (int k = 0; k < 2; ++k) dst[n][k] = *(const PG8_LAS bf16x8*)(lds + PG8_SB(b, h) + boff + n * 2048 + k * 1024); } while (0)
; #define PG8_MMA(ai, bj, At, Bt) do { __builtin_amdgcn_s_setprio(1); _Pragma("unroll") for (int m = 0; m < 4; ++m) _Pragma("unroll") for (int n = 0; n < 2; ++n) _Pragma("unroll") for (int k = 0; k < 2; ++k) \
;         acc[ai][bj][m][n] = __builtin_amdgcn_mfma_f32_16x16x32_bf16(Bt[n][k], At[m][k], acc[ai][bj][m][n], 0, 0, 0); __builtin_amdgcn_s_setprio(0); } while (0)
; #define PG8_WAIT_V(n) asm volatile("s_waitcnt vmcnt(" #n ")" ::: "memory")
; #define PG8_WAIT_L(n) asm volatile("s_waitcnt lgkmcnt(" #n ")" ::: "memory")
; #define PG8_BAR __builtin_amdgcn_s_barrier()
; template <class Epi, class Sched, bool ALIGN_EPI = false, bool SP2 = false>
; __device__ __forceinline__ void gemm_phase(PG8_LAS unsigned char* lds, const Gemm g, const Sched& S, const Epi& E, const int wave_in) {
;     ...
;         for (int t = 0; t < nt; t += 2) {
;             const bool last = (t == nt - 2);
;             const char* a1 = cA + (size_t)(t + 1) * kstep;
;             const char* a2 = last ? nA : cA + (size_t)(t + 2) * kstep; const char* b2 = last ? nB : cB + (size_t)(t + 2) * kstep;
;             const char* a3 = a2 + kstep; const char* b3 = b2 + kstep;
;             if (last && has_next) S.a_ready(nxt);
;             if constexpr (SP2) {
;             PG8_LDB(B0, 0, 0); PG8_LDB(B1, 0, 1); PG8_SCHED; PG8_LDA(At, 0, 0); PG8_STAGE(PG8_SA(1, 1), a1 + hstepA, voffA);
;             PG8_WAIT_V(8); PG8_WAIT_L(0); PG8_BAR; PG8_MMA(0, 0, At, B0); PG8_MMA(0, 1, At, B1); PG8_BAR; PG8_SCHED;
;             PG8_LDA(At, 0, 1); PG8_STAGE(PG8_SB(0, 0), b2, voffB); PG8_STAGE(PG8_SB(0, 1), b2 + hstepB, voffB); PG8_STAGE(PG8_SA(0, 0), a2, voffA);
.LBB0_2577:
	ds_read_b128 v[64:67], v189
	ds_read_b128 v[68:71], v189 offset:1024
	ds_read_b128 v[72:75], v189 offset:2048
	ds_read_b128 v[76:79], v189 offset:3072
	ds_read_b128 v[80:83], v197
	ds_read_b128 v[84:87], v197 offset:1024
	ds_read_b128 v[88:91], v197 offset:2048
	ds_read_b128 v[92:95], v197 offset:3072
	s_add_u32 s48, s46, 0xfff80080
	s_addc_u32 s49, s47, -1
	s_cmp_eq_u32 s75, 28
	s_cselect_b32 s51, s11, s49
	s_cselect_b32 s50, s39, s48
	s_cselect_b32 s49, s37, s73
	s_cselect_b32 s48, s45, s72
	v_lshl_add_u64 v[224:225], s[46:47], 0, v[206:207]
	s_add_i32 m0, s57, 0xc000
	ds_read_b128 v[96:99], v199
	ds_read_b128 v[100:103], v199 offset:1024
	ds_read_b128 v[104:107], v199 offset:2048
	ds_read_b128 v[108:111], v199 offset:3072
	ds_read_b128 v[176:179], v199 offset:4096
	ds_read_b128 v[212:215], v199 offset:5120
	ds_read_b128 v[216:219], v199 offset:6144
	ds_read_b128 v[220:223], v199 offset:7168
	global_load_lds_dwordx4 v[224:225], off
	v_lshl_add_u64 v[224:225], s[46:47], 0, v[208:209]
	s_add_i32 m0, s57, 0xe000
	s_nop 0
	global_load_lds_dwordx4 v[224:225], off
	s_waitcnt vmcnt(8)
	s_waitcnt lgkmcnt(0)
	s_barrier
	s_setprio 1
	s_waitcnt lgkmcnt(0)
	v_mfma_f32_16x16x32_bf16 v[172:175], v[64:67], v[96:99], v[172:175]
	v_mfma_f32_16x16x32_bf16 v[164:167], v[72:75], v[96:99], v[164:167]
	v_mfma_f32_16x16x32_bf16 v[156:159], v[64:67], v[104:107], v[156:159]
	v_mfma_f32_16x16x32_bf16 v[148:151], v[72:75], v[104:107], v[148:151]
	v_mfma_f32_16x16x32_bf16 v[140:143], v[64:67], v[176:179], v[140:143]
	v_mfma_f32_16x16x32_bf16 v[132:135], v[72:75], v[176:179], v[132:135]
	v_mfma_f32_16x16x32_bf16 v[124:127], v[64:67], v[216:219], v[124:127]
	v_mfma_f32_16x16x32_bf16 v[120:123], v[72:75], v[216:219], v[120:123]
	v_mfma_f32_16x16x32_bf16 v[172:175], v[68:71], v[100:103], v[172:175]
	v_mfma_f32_16x16x32_bf16 v[164:167], v[76:79], v[100:103], v[164:167]
	v_mfma_f32_16x16x32_bf16 v[156:159], v[68:71], v[108:111], v[156:159]
	v_mfma_f32_16x16x32_bf16 v[148:151], v[76:79], v[108:111], v[148:151]
	v_mfma_f32_16x16x32_bf16 v[140:143], v[68:71], v[212:215], v[140:143]
	v_mfma_f32_16x16x32_bf16 v[132:135], v[76:79], v[212:215], v[132:135]
	v_mfma_f32_16x16x32_bf16 v[124:127], v[68:71], v[220:223], v[124:127]
	v_mfma_f32_16x16x32_bf16 v[120:123], v[76:79], v[220:223], v[120:123]
	s_setprio 0
	s_setprio 1
	v_mfma_f32_16x16x32_bf16 v[168:171], v[80:83], v[96:99], v[168:171]
	v_mfma_f32_16x16x32_bf16 v[96:99], v[88:91], v[96:99], v[160:163]
	v_mfma_f32_16x16x32_bf16 v[168:171], v[84:87], v[100:103], v[168:171]
	v_mfma_f32_16x16x32_bf16 v[96:99], v[92:95], v[100:103], v[96:99]
	v_mfma_f32_16x16x32_bf16 v[100:103], v[80:83], v[104:107], v[152:155]
	v_mfma_f32_16x16x32_bf16 v[104:107], v[88:91], v[104:107], v[144:147]
	v_mfma_f32_16x16x32_bf16 v[128:131], v[88:91], v[176:179], v[128:131]
	v_mfma_f32_16x16x32_bf16 v[116:119], v[80:83], v[216:219], v[116:119]
	v_mfma_f32_16x16x32_bf16 v[112:115], v[88:91], v[216:219], v[112:115]
	v_mfma_f32_16x16x32_bf16 v[100:103], v[84:87], v[108:111], v[100:103]
	v_mfma_f32_16x16x32_bf16 v[104:107], v[92:95], v[108:111], v[104:107]
	v_mfma_f32_16x16x32_bf16 v[108:111], v[80:83], v[176:179], v[136:139]
	v_mfma_f32_16x16x32_bf16 v[128:131], v[92:95], v[212:215], v[128:131]
	v_mfma_f32_16x16x32_bf16 v[116:119], v[84:87], v[220:223], v[116:119]
	v_mfma_f32_16x16x32_bf16 v[112:115], v[92:95], v[220:223], v[112:115]
	v_mfma_f32_16x16x32_bf16 v[108:111], v[84:87], v[212:215], v[108:111]
	s_setprio 0
	s_barrier
	s_add_i32 s76, s69, s56
	v_lshl_add_u64 v[232:233], s[48:49], 0, v[182:183]
	s_mov_b32 m0, s76
	ds_read_b128 v[136:139], v199 offset:16384
	ds_read_b128 v[144:147], v199 offset:17408
	ds_read_b128 v[152:155], v199 offset:18432
	ds_read_b128 v[160:163], v199 offset:19456
	ds_read_b128 v[176:179], v199 offset:20480
	ds_read_b128 v[212:215], v199 offset:21504
	ds_read_b128 v[216:219], v199 offset:22528
	ds_read_b128 v[220:223], v199 offset:23552
	global_load_lds_dwordx4 v[232:233], off
	s_add_i32 m0, s76, 0x2000
	s_add_u32 s76, s48, 0x80000
	v_lshl_add_u64 v[234:235], s[48:49], 0, v[186:187]
	s_addc_u32 s77, s49, 0
	s_add_i32 s78, s70, s56
	global_load_lds_dwordx4 v[234:235], off
	v_lshl_add_u64 v[224:225], s[76:77], 0, v[182:183]
	s_mov_b32 m0, s78
	v_lshl_add_u64 v[236:237], s[50:51], 0, v[180:181]
	global_load_lds_dwordx4 v[224:225], off
	v_lshl_add_u64 v[224:225], s[76:77], 0, v[186:187]
	s_add_i32 m0, s78, 0x2000
	v_lshl_add_u64 v[238:239], s[50:51], 0, v[184:185]
	global_load_lds_dwordx4 v[224:225], off
	s_mov_b32 m0, s57
	s_nop 0
	global_load_lds_dwordx4 v[236:237], off
	s_mov_b32 m0, s58
	s_nop 0
	global_load_lds_dwordx4 v[238:239], off
	s_waitcnt vmcnt(8)
	s_waitcnt lgkmcnt(0)
	s_barrier
; #define PG8_STAGE(bufoff, gbase, voff) do { _Pragma("unroll") for (int _i = 0; _i < 2; ++_i) \
;         __builtin_amdgcn_global_load_lds((const unsigned*)((const char*)(gbase) + (voff)[_i]), (PG8_LAS unsigned*)(lds + (bufoff) + ldsw + _i * 8192), 16, 0, 0); } while (0)
; #define PG8_LDA(dst, b, h) do { _Pragma("unroll") for (int m = 0; m < 4; ++m) _Pragma("unroll") for (int k = 0; k < 2; ++k) dst[m][k] = *(const PG8_LAS bf16x8*)(lds + PG8_SA(b, h) + aoff + m * 2048 + k * 1024); } while (0)
; #define PG8_LDB(dst, b, h) do { _Pragma("unroll") for (int n = 0; n < 2; ++n) _Pragma("unroll") for (int k = 0; k < 2; ++k) dst[n][k] = *(const PG8_LAS bf16x8*)(lds + PG8_SB(b, h) + boff + n * 2048 + k * 1024); } while (0)
; #define PG8_MMA(ai, bj, At, Bt) do { __builtin_amdgcn_s_setprio(1); _Pragma("unroll") for (int m = 0; m < 4; ++m) _Pragma("unroll") for (int n = 0; n < 2; ++n) _Pragma("unroll") for (int k = 0; k < 2; ++k) \
;         acc[ai][bj][m][n] = __builtin_amdgcn_mfma_f32_16x16x32_bf16(Bt[n][k], At[m][k], acc[ai][bj][m][n], 0, 0, 0); __builtin_amdgcn_s_setprio(0); } while (0)
; #define PG8_WAIT_V(n) asm volatile("s_waitcnt vmcnt(" #n ")" ::: "memory")
; #define PG8_WAIT_L(n) asm volatile("s_waitcnt lgkmcnt(" #n ")" ::: "memory")
; #define PG8_BAR __builtin_amdgcn_s_barrier()
; #define PG8_SCHED __builtin_amdgcn_sched_barrier(0)
; template <class Epi, class Sched, bool ALIGN_EPI = false, bool SP2 = false>
; __device__ __forceinline__ void gemm_phase(PG8_LAS unsigned char* lds, const Gemm g, const Sched& S, const Epi& E, const int wave_in) {
;     ...
;             PG8_WAIT_V(8); PG8_WAIT_L(0); PG8_BAR; PG8_MMA(1, 0, At, B0); PG8_MMA(1, 1, At, B1); PG8_BAR; PG8_SCHED;
;             PG8_LDB(B0, 1, 0); PG8_LDB(B1, 1, 1); PG8_SCHED; PG8_LDA(At, 1, 0); PG8_STAGE(PG8_SA(0, 1), a2 + hstepA, voffA);
;             PG8_WAIT_V(8); PG8_WAIT_L(0); PG8_BAR; PG8_MMA(0, 0, At, B0); PG8_MMA(0, 1, At, B1); PG8_BAR; PG8_SCHED;
	s_setprio 1
	s_waitcnt lgkmcnt(0)
	v_mfma_f32_16x16x32_bf16 v[60:63], v[64:67], v[136:139], v[60:63]
	v_mfma_f32_16x16x32_bf16 v[52:55], v[72:75], v[136:139], v[52:55]
	v_mfma_f32_16x16x32_bf16 v[44:47], v[64:67], v[152:155], v[44:47]
	v_mfma_f32_16x16x32_bf16 v[36:39], v[72:75], v[152:155], v[36:39]
	v_mfma_f32_16x16x32_bf16 v[28:31], v[64:67], v[176:179], v[28:31]
	v_mfma_f32_16x16x32_bf16 v[20:23], v[72:75], v[176:179], v[20:23]
	v_mfma_f32_16x16x32_bf16 v[12:15], v[64:67], v[216:219], v[12:15]
	v_mfma_f32_16x16x32_bf16 v[8:11], v[72:75], v[216:219], v[8:11]
	v_mfma_f32_16x16x32_bf16 v[60:63], v[68:71], v[144:147], v[60:63]
	v_mfma_f32_16x16x32_bf16 v[52:55], v[76:79], v[144:147], v[52:55]
	v_mfma_f32_16x16x32_bf16 v[44:47], v[68:71], v[160:163], v[44:47]
	v_mfma_f32_16x16x32_bf16 v[36:39], v[76:79], v[160:163], v[36:39]
	v_mfma_f32_16x16x32_bf16 v[28:31], v[68:71], v[212:215], v[28:31]
	v_mfma_f32_16x16x32_bf16 v[20:23], v[76:79], v[212:215], v[20:23]
	v_mfma_f32_16x16x32_bf16 v[12:15], v[68:71], v[220:223], v[12:15]
	v_mfma_f32_16x16x32_bf16 v[8:11], v[76:79], v[220:223], v[8:11]
	s_setprio 0
	s_setprio 1
	v_mfma_f32_16x16x32_bf16 v[56:59], v[80:83], v[136:139], v[56:59]
	v_mfma_f32_16x16x32_bf16 v[48:51], v[88:91], v[136:139], v[48:51]
	v_mfma_f32_16x16x32_bf16 v[40:43], v[80:83], v[152:155], v[40:43]
	v_mfma_f32_16x16x32_bf16 v[32:35], v[88:91], v[152:155], v[32:35]
	v_mfma_f32_16x16x32_bf16 v[24:27], v[80:83], v[176:179], v[24:27]
	v_mfma_f32_16x16x32_bf16 v[16:19], v[88:91], v[176:179], v[16:19]
	v_mfma_f32_16x16x32_bf16 v[4:7], v[80:83], v[216:219], v[4:7]
	v_mfma_f32_16x16x32_bf16 v[0:3], v[88:91], v[216:219], v[0:3]
	v_mfma_f32_16x16x32_bf16 v[56:59], v[84:87], v[144:147], v[56:59]
	v_mfma_f32_16x16x32_bf16 v[48:51], v[92:95], v[144:147], v[48:51]
	v_mfma_f32_16x16x32_bf16 v[40:43], v[84:87], v[160:163], v[40:43]
	v_mfma_f32_16x16x32_bf16 v[32:35], v[92:95], v[160:163], v[32:35]
	v_mfma_f32_16x16x32_bf16 v[24:27], v[84:87], v[212:215], v[24:27]
	v_mfma_f32_16x16x32_bf16 v[16:19], v[92:95], v[212:215], v[16:19]
	v_mfma_f32_16x16x32_bf16 v[4:7], v[84:87], v[220:223], v[4:7]
	v_mfma_f32_16x16x32_bf16 v[0:3], v[92:95], v[220:223], v[0:3]
	s_setprio 0
	s_barrier
	s_add_i32 s76, 0, 0x18000
	s_add_i32 s77, 0, 0x1c000
	v_add_u32_e32 v76, s76, v195
	v_add_u32_e32 v92, s77, v195
	ds_read_b128 v[64:67], v76
	ds_read_b128 v[68:71], v76 offset:1024
	ds_read_b128 v[72:75], v76 offset:2048
	ds_read_b128 v[76:79], v76 offset:3072
	ds_read_b128 v[80:83], v92
	ds_read_b128 v[84:87], v92 offset:1024
	ds_read_b128 v[88:91], v92 offset:2048
	ds_read_b128 v[92:95], v92 offset:3072
	s_add_u32 s50, s50, 0x80000
	s_addc_u32 s51, s51, 0
	s_mov_b32 m0, s59
	v_lshl_add_u64 v[152:153], s[50:51], 0, v[180:181]
	ds_read_b128 v[136:139], v199 offset:32768
	ds_read_b128 v[144:147], v199 offset:33792
	ds_read_b128 v[176:179], v199 offset:34816
	ds_read_b128 v[212:215], v199 offset:35840
	ds_read_b128 v[216:219], v199 offset:36864
	ds_read_b128 v[220:223], v199 offset:37888
	ds_read_b128 v[224:227], v199 offset:38912
	ds_read_b128 v[228:231], v199 offset:39936
	global_load_lds_dwordx4 v[152:153], off
	v_lshl_add_u64 v[152:153], s[50:51], 0, v[184:185]
	s_mov_b32 m0, s60
	s_nop 0
	global_load_lds_dwordx4 v[152:153], off
	s_waitcnt vmcnt(8)
	s_waitcnt lgkmcnt(0)
	s_barrier
	s_setprio 1
	s_waitcnt lgkmcnt(0)
	v_mfma_f32_16x16x32_bf16 v[152:155], v[64:67], v[136:139], v[172:175]
	v_mfma_f32_16x16x32_bf16 v[172:175], v[68:71], v[144:147], v[152:155]
	v_mfma_f32_16x16x32_bf16 v[152:155], v[72:75], v[136:139], v[164:167]
	v_mfma_f32_16x16x32_bf16 v[164:167], v[76:79], v[144:147], v[152:155]
	v_mfma_f32_16x16x32_bf16 v[152:155], v[64:67], v[176:179], v[156:159]
	v_mfma_f32_16x16x32_bf16 v[148:151], v[72:75], v[176:179], v[148:151]
	v_mfma_f32_16x16x32_bf16 v[140:143], v[64:67], v[216:219], v[140:143]
	v_mfma_f32_16x16x32_bf16 v[132:135], v[72:75], v[216:219], v[132:135]
	v_mfma_f32_16x16x32_bf16 v[124:127], v[64:67], v[224:227], v[124:127]
	v_mfma_f32_16x16x32_bf16 v[120:123], v[72:75], v[224:227], v[120:123]
	v_mfma_f32_16x16x32_bf16 v[156:159], v[68:71], v[212:215], v[152:155]
	v_mfma_f32_16x16x32_bf16 v[148:151], v[76:79], v[212:215], v[148:151]
	v_mfma_f32_16x16x32_bf16 v[140:143], v[68:71], v[220:223], v[140:143]
	v_mfma_f32_16x16x32_bf16 v[132:135], v[76:79], v[220:223], v[132:135]
	v_mfma_f32_16x16x32_bf16 v[124:127], v[68:71], v[228:231], v[124:127]
	v_mfma_f32_16x16x32_bf16 v[120:123], v[76:79], v[228:231], v[120:123]
	s_setprio 0
	s_setprio 1
	v_mfma_f32_16x16x32_bf16 v[96:99], v[88:91], v[136:139], v[96:99]
	v_mfma_f32_16x16x32_bf16 v[152:155], v[80:83], v[136:139], v[168:171]
	v_mfma_f32_16x16x32_bf16 v[160:163], v[92:95], v[144:147], v[96:99]
	v_mfma_f32_16x16x32_bf16 v[96:99], v[80:83], v[176:179], v[100:103]
	v_mfma_f32_16x16x32_bf16 v[168:171], v[84:87], v[144:147], v[152:155]
	v_mfma_f32_16x16x32_bf16 v[152:155], v[84:87], v[212:215], v[96:99]
	v_mfma_f32_16x16x32_bf16 v[96:99], v[88:91], v[176:179], v[104:107]
	v_mfma_f32_16x16x32_bf16 v[144:147], v[92:95], v[212:215], v[96:99]
	v_mfma_f32_16x16x32_bf16 v[96:99], v[80:83], v[216:219], v[108:111]
	v_mfma_f32_16x16x32_bf16 v[136:139], v[84:87], v[220:223], v[96:99]
	v_mfma_f32_16x16x32_bf16 v[96:99], v[88:91], v[216:219], v[128:131]
	v_mfma_f32_16x16x32_bf16 v[128:131], v[92:95], v[220:223], v[96:99]
	v_mfma_f32_16x16x32_bf16 v[96:99], v[80:83], v[224:227], v[116:119]
	v_mfma_f32_16x16x32_bf16 v[116:119], v[84:87], v[228:231], v[96:99]
	v_mfma_f32_16x16x32_bf16 v[96:99], v[88:91], v[224:227], v[112:115]
	v_mfma_f32_16x16x32_bf16 v[112:115], v[92:95], v[228:231], v[96:99]
	s_setprio 0
	s_barrier
; #define PG8_STAGE(bufoff, gbase, voff) do { _Pragma("unroll") for (int _i = 0; _i < 2; ++_i) \
;         __builtin_amdgcn_global_load_lds((const unsigned*)((const char*)(gbase) + (voff)[_i]), (PG8_LAS unsigned*)(lds + (bufoff) + ldsw + _i * 8192), 16, 0, 0); } while (0)
; #define PG8_LDA(dst, b, h) do { _Pragma("unroll") for (int m = 0; m < 4; ++m) _Pragma("unroll") for (int k = 0; k < 2; ++k) dst[m][k] = *(const PG8_LAS bf16x8*)(lds + PG8_SA(b, h) + aoff + m * 2048 + k * 1024); } while (0)
; #define PG8_MMA(ai, bj, At, Bt) do { __builtin_amdgcn_s_setprio(1); _Pragma("unroll") for (int m = 0; m < 4; ++m) _Pragma("unroll") for (int n = 0; n < 2; ++n) _Pragma("unroll") for (int k = 0; k < 2; ++k) \
;         acc[ai][bj][m][n] = __builtin_amdgcn_mfma_f32_16x16x32_bf16(Bt[n][k], At[m][k], acc[ai][bj][m][n], 0, 0, 0); __builtin_amdgcn_s_setprio(0); } while (0)
; #define PG8_WAIT_V(n) asm volatile("s_waitcnt vmcnt(" #n ")" ::: "memory")
; #define PG8_WAIT_L(n) asm volatile("s_waitcnt lgkmcnt(" #n ")" ::: "memory")
; #define PG8_BAR __builtin_amdgcn_s_barrier()
; #define PG8_SCHED __builtin_amdgcn_sched_barrier(0)
; template <class Epi, class Sched, bool ALIGN_EPI = false, bool SP2 = false>
; __device__ __forceinline__ void gemm_phase(PG8_LAS unsigned char* lds, const Gemm g, const Sched& S, const Epi& E, const int wave_in) {
;     ...
;         for (int t = 0; t < nt; t += 2) {
;             const bool last = (t == nt - 2);
;     ...
;             PG8_LDA(At, 1, 1); PG8_STAGE(PG8_SB(1, 0), b3, voffB); PG8_STAGE(PG8_SB(1, 1), b3 + hstepB, voffB); PG8_STAGE(PG8_SA(1, 0), a3, voffA);
;             PG8_WAIT_V(8); PG8_WAIT_L(0); PG8_BAR; PG8_MMA(1, 0, At, B0); PG8_MMA(1, 1, At, B1); PG8_BAR; PG8_SCHED;
	s_add_i32 s50, s76, s56
	v_lshl_add_u64 v[224:225], v[232:233], 0, s[20:21]
	s_mov_b32 m0, s50
	s_nop 1
	ds_read_b128 v[96:99], v199 offset:49152
	ds_read_b128 v[100:103], v199 offset:50176
	ds_read_b128 v[104:107], v199 offset:51200
	ds_read_b128 v[108:111], v199 offset:52224
	ds_read_b128 v[176:179], v199 offset:53248
	ds_read_b128 v[212:215], v199 offset:54272
	ds_read_b128 v[216:219], v199 offset:55296
	ds_read_b128 v[220:223], v199 offset:56320
	global_load_lds_dwordx4 v[224:225], off
	s_add_i32 m0, s50, 0x2000
	s_add_u32 s48, s48, 0x80080
	v_lshl_add_u64 v[224:225], v[234:235], 0, s[20:21]
	s_addc_u32 s49, s49, 0
	s_add_i32 s50, s77, s56
	global_load_lds_dwordx4 v[224:225], off
	v_lshl_add_u64 v[224:225], s[48:49], 0, v[182:183]
	s_mov_b32 m0, s50
	s_nop 0
	global_load_lds_dwordx4 v[224:225], off
	v_lshl_add_u64 v[224:225], s[48:49], 0, v[186:187]
	s_add_i32 m0, s50, 0x2000
	s_nop 0
	global_load_lds_dwordx4 v[224:225], off
	v_lshl_add_u64 v[224:225], v[236:237], 0, s[20:21]
	s_mov_b32 m0, s63
	s_nop 0
	global_load_lds_dwordx4 v[224:225], off
	v_lshl_add_u64 v[224:225], v[238:239], 0, s[20:21]
	s_mov_b32 m0, s64
	s_nop 0
	global_load_lds_dwordx4 v[224:225], off
	s_waitcnt vmcnt(8)
	s_waitcnt lgkmcnt(0)
	s_barrier
	s_setprio 1
	s_waitcnt lgkmcnt(0)
	v_mfma_f32_16x16x32_bf16 v[60:63], v[64:67], v[96:99], v[60:63]
	v_mfma_f32_16x16x32_bf16 v[52:55], v[72:75], v[96:99], v[52:55]
	v_mfma_f32_16x16x32_bf16 v[44:47], v[64:67], v[104:107], v[44:47]
	v_mfma_f32_16x16x32_bf16 v[36:39], v[72:75], v[104:107], v[36:39]
	v_mfma_f32_16x16x32_bf16 v[28:31], v[64:67], v[176:179], v[28:31]
	v_mfma_f32_16x16x32_bf16 v[20:23], v[72:75], v[176:179], v[20:23]
	v_mfma_f32_16x16x32_bf16 v[12:15], v[64:67], v[216:219], v[12:15]
	v_mfma_f32_16x16x32_bf16 v[8:11], v[72:75], v[216:219], v[8:11]
	v_mfma_f32_16x16x32_bf16 v[60:63], v[68:71], v[100:103], v[60:63]
	v_mfma_f32_16x16x32_bf16 v[52:55], v[76:79], v[100:103], v[52:55]
	v_mfma_f32_16x16x32_bf16 v[44:47], v[68:71], v[108:111], v[44:47]
	v_mfma_f32_16x16x32_bf16 v[36:39], v[76:79], v[108:111], v[36:39]
	v_mfma_f32_16x16x32_bf16 v[28:31], v[68:71], v[212:215], v[28:31]
	v_mfma_f32_16x16x32_bf16 v[20:23], v[76:79], v[212:215], v[20:23]
	v_mfma_f32_16x16x32_bf16 v[12:15], v[68:71], v[220:223], v[12:15]
	v_mfma_f32_16x16x32_bf16 v[8:11], v[76:79], v[220:223], v[8:11]
	s_setprio 0
	s_setprio 1
	v_mfma_f32_16x16x32_bf16 v[56:59], v[80:83], v[96:99], v[56:59]
	v_mfma_f32_16x16x32_bf16 v[48:51], v[88:91], v[96:99], v[48:51]
	v_mfma_f32_16x16x32_bf16 v[40:43], v[80:83], v[104:107], v[40:43]
	v_mfma_f32_16x16x32_bf16 v[32:35], v[88:91], v[104:107], v[32:35]
	v_mfma_f32_16x16x32_bf16 v[24:27], v[80:83], v[176:179], v[24:27]
	v_mfma_f32_16x16x32_bf16 v[16:19], v[88:91], v[176:179], v[16:19]
	v_mfma_f32_16x16x32_bf16 v[4:7], v[80:83], v[216:219], v[4:7]
	v_mfma_f32_16x16x32_bf16 v[0:3], v[88:91], v[216:219], v[0:3]
	v_mfma_f32_16x16x32_bf16 v[56:59], v[84:87], v[100:103], v[56:59]
	v_mfma_f32_16x16x32_bf16 v[48:51], v[92:95], v[100:103], v[48:51]
	v_mfma_f32_16x16x32_bf16 v[40:43], v[84:87], v[108:111], v[40:43]
	v_mfma_f32_16x16x32_bf16 v[32:35], v[92:95], v[108:111], v[32:35]
	v_mfma_f32_16x16x32_bf16 v[24:27], v[84:87], v[212:215], v[24:27]
	v_mfma_f32_16x16x32_bf16 v[16:19], v[92:95], v[212:215], v[16:19]
	v_mfma_f32_16x16x32_bf16 v[4:7], v[84:87], v[220:223], v[4:7]
	v_mfma_f32_16x16x32_bf16 v[0:3], v[92:95], v[220:223], v[0:3]
	s_setprio 0
	s_add_i32 s75, s75, 2
	s_add_u32 s46, s46, 0x100
	s_addc_u32 s47, s47, 0
	s_add_u32 s72, s72, 0x100
	s_addc_u32 s73, s73, 0
	s_cmp_gt_u32 s75, 29
	s_barrier
	s_cbranch_scc0 .LBB0_2577
	s_and_b64 vcc, exec, s[22:23]
	s_cbranch_vccz .LBB0_2580
	s_barrier
